# GEMM K-loops: static priority 1 for waves 4-7, no per-MMA toggles
# baseline (speedup 1.0000x reference)
.LBB0_222:
	s_cmp_lt_u32 s33, 256
	s_cbranch_scc1 .Lsp_g1
	s_setprio 1

.LBB0_225:
	ds_read_b128 v[132:135], v142
	ds_read_b128 v[136:139], v142 offset:1024
	ds_read_b128 v[150:153], v142 offset:2048
	ds_read_b128 v[154:157], v142 offset:3072
	s_add_i32 s69, s8, s68
	s_add_i32 s70, s69, 0x80080
	s_mov_b32 m0, s7
	ds_read_b128 v[158:161], v143
	ds_read_b128 v[162:165], v143 offset:1024
	ds_read_b128 v[166:169], v144
	ds_read_b128 v[170:173], v144 offset:1024
	ds_read_b128 v[178:181], v145
	ds_read_b128 v[214:217], v145 offset:1024
	ds_read_b128 v[218:221], v146
	ds_read_b128 v[222:225], v146 offset:1024
	buffer_load_dwordx4 v140, s[48:51], s70 offen lds
	s_mov_b32 m0, s6
	s_nop 0
	buffer_load_dwordx4 v141, s[48:51], s70 offen lds
	s_waitcnt lgkmcnt(8)
	s_barrier
	s_waitcnt lgkmcnt(0)
	s_waitcnt lgkmcnt(0)
	v_mfma_f32_16x16x32_bf16 v[126:129], v[132:135], v[158:161], v[126:129]
	v_mfma_f32_16x16x32_bf16 v[122:125], v[150:153], v[158:161], v[122:125]
	v_mfma_f32_16x16x32_bf16 v[118:121], v[132:135], v[166:169], v[118:121]
	v_mfma_f32_16x16x32_bf16 v[114:117], v[150:153], v[166:169], v[114:117]
	v_mfma_f32_16x16x32_bf16 v[110:113], v[132:135], v[178:181], v[110:113]
	v_mfma_f32_16x16x32_bf16 v[106:109], v[150:153], v[178:181], v[106:109]
	v_mfma_f32_16x16x32_bf16 v[102:105], v[132:135], v[218:221], v[102:105]
	v_mfma_f32_16x16x32_bf16 v[98:101], v[150:153], v[218:221], v[98:101]
	v_mfma_f32_16x16x32_bf16 v[126:129], v[136:139], v[162:165], v[126:129]
	v_mfma_f32_16x16x32_bf16 v[122:125], v[154:157], v[162:165], v[122:125]
	v_mfma_f32_16x16x32_bf16 v[118:121], v[136:139], v[170:173], v[118:121]
	v_mfma_f32_16x16x32_bf16 v[114:117], v[154:157], v[170:173], v[114:117]
	v_mfma_f32_16x16x32_bf16 v[110:113], v[136:139], v[214:217], v[110:113]
	v_mfma_f32_16x16x32_bf16 v[106:109], v[154:157], v[214:217], v[106:109]
	v_mfma_f32_16x16x32_bf16 v[102:105], v[136:139], v[222:225], v[102:105]
	v_mfma_f32_16x16x32_bf16 v[98:101], v[154:157], v[222:225], v[98:101]
	s_barrier
	s_add_i32 s70, s9, s68
	s_add_i32 s71, s70, 0x100
	s_mov_b32 m0, s28
	ds_read_b128 v[226:229], v147
	ds_read_b128 v[230:233], v147 offset:1024
	ds_read_b128 v[234:237], v147 offset:2048
	ds_read_b128 v[238:241], v147 offset:3072
	buffer_load_dwordx4 v140, s[44:47], s71 offen lds
	s_mov_b32 m0, s29
	s_nop 0
	buffer_load_dwordx4 v141, s[44:47], s71 offen lds
	s_barrier
	s_waitcnt lgkmcnt(0)
	s_waitcnt lgkmcnt(0)
	v_mfma_f32_16x16x32_bf16 v[94:97], v[226:229], v[158:161], v[94:97]
	v_mfma_f32_16x16x32_bf16 v[90:93], v[234:237], v[158:161], v[90:93]
	v_mfma_f32_16x16x32_bf16 v[86:89], v[226:229], v[166:169], v[86:89]
	v_mfma_f32_16x16x32_bf16 v[82:85], v[234:237], v[166:169], v[82:85]
	v_mfma_f32_16x16x32_bf16 v[78:81], v[226:229], v[178:181], v[78:81]
	v_mfma_f32_16x16x32_bf16 v[74:77], v[234:237], v[178:181], v[74:77]
	v_mfma_f32_16x16x32_bf16 v[70:73], v[226:229], v[218:221], v[70:73]
	v_mfma_f32_16x16x32_bf16 v[66:69], v[234:237], v[218:221], v[66:69]
	v_mfma_f32_16x16x32_bf16 v[94:97], v[230:233], v[162:165], v[94:97]
	v_mfma_f32_16x16x32_bf16 v[90:93], v[238:241], v[162:165], v[90:93]
	v_mfma_f32_16x16x32_bf16 v[86:89], v[230:233], v[170:173], v[86:89]
	v_mfma_f32_16x16x32_bf16 v[82:85], v[238:241], v[170:173], v[82:85]
	v_mfma_f32_16x16x32_bf16 v[78:81], v[230:233], v[214:217], v[78:81]
	v_mfma_f32_16x16x32_bf16 v[74:77], v[238:241], v[214:217], v[74:77]
	v_mfma_f32_16x16x32_bf16 v[70:73], v[230:233], v[222:225], v[70:73]
	v_mfma_f32_16x16x32_bf16 v[66:69], v[238:241], v[222:225], v[66:69]
	s_add_i32 s71, s69, 0x100
	s_mov_b32 m0, s27
	s_barrier
	ds_read_b128 v[158:161], v143 offset:16384
	ds_read_b128 v[162:165], v143 offset:17408
	ds_read_b128 v[166:169], v144 offset:16384
	ds_read_b128 v[170:173], v144 offset:17408
	ds_read_b128 v[178:181], v145 offset:16384
	ds_read_b128 v[214:217], v145 offset:17408
	ds_read_b128 v[218:221], v146 offset:16384
	ds_read_b128 v[222:225], v146 offset:17408
	buffer_load_dwordx4 v140, s[48:51], s71 offen lds
	s_mov_b32 m0, s30
	s_nop 0
	buffer_load_dwordx4 v141, s[48:51], s71 offen lds
	s_barrier
	s_waitcnt lgkmcnt(0)
	s_waitcnt lgkmcnt(0)
	v_mfma_f32_16x16x32_bf16 v[62:65], v[132:135], v[158:161], v[62:65]
	v_mfma_f32_16x16x32_bf16 v[58:61], v[150:153], v[158:161], v[58:61]
	v_mfma_f32_16x16x32_bf16 v[54:57], v[132:135], v[166:169], v[54:57]
	v_mfma_f32_16x16x32_bf16 v[50:53], v[150:153], v[166:169], v[50:53]
	v_mfma_f32_16x16x32_bf16 v[46:49], v[132:135], v[178:181], v[46:49]
	v_mfma_f32_16x16x32_bf16 v[42:45], v[150:153], v[178:181], v[42:45]
	v_mfma_f32_16x16x32_bf16 v[38:41], v[132:135], v[218:221], v[38:41]
	v_mfma_f32_16x16x32_bf16 v[34:37], v[150:153], v[218:221], v[34:37]
	v_mfma_f32_16x16x32_bf16 v[62:65], v[136:139], v[162:165], v[62:65]
	v_mfma_f32_16x16x32_bf16 v[58:61], v[154:157], v[162:165], v[58:61]
	v_mfma_f32_16x16x32_bf16 v[54:57], v[136:139], v[170:173], v[54:57]
	v_mfma_f32_16x16x32_bf16 v[50:53], v[154:157], v[170:173], v[50:53]
	v_mfma_f32_16x16x32_bf16 v[46:49], v[136:139], v[214:217], v[46:49]
	v_mfma_f32_16x16x32_bf16 v[42:45], v[154:157], v[214:217], v[42:45]
	v_mfma_f32_16x16x32_bf16 v[38:41], v[136:139], v[222:225], v[38:41]
	v_mfma_f32_16x16x32_bf16 v[34:37], v[154:157], v[222:225], v[34:37]
	s_barrier
	s_add_i32 s71, s70, 0x80100
	s_mov_b32 m0, s31
	s_nop 0
	buffer_load_dwordx4 v140, s[44:47], s71 offen lds
	s_mov_b32 m0, s34
	s_nop 0
	buffer_load_dwordx4 v141, s[44:47], s71 offen lds
	s_waitcnt vmcnt(6)
	s_barrier
	v_mfma_f32_16x16x32_bf16 v[30:33], v[226:229], v[158:161], v[30:33]
	v_mfma_f32_16x16x32_bf16 v[26:29], v[234:237], v[158:161], v[26:29]
	v_mfma_f32_16x16x32_bf16 v[22:25], v[226:229], v[166:169], v[22:25]
	v_mfma_f32_16x16x32_bf16 v[18:21], v[234:237], v[166:169], v[18:21]
	v_mfma_f32_16x16x32_bf16 v[12:15], v[226:229], v[178:181], v[12:15]
	v_mfma_f32_16x16x32_bf16 v[8:11], v[234:237], v[178:181], v[8:11]
	v_mfma_f32_16x16x32_bf16 v[4:7], v[226:229], v[218:221], v[4:7]
	v_mfma_f32_16x16x32_bf16 v[0:3], v[234:237], v[218:221], v[0:3]
	v_mfma_f32_16x16x32_bf16 v[30:33], v[230:233], v[162:165], v[30:33]
	v_mfma_f32_16x16x32_bf16 v[26:29], v[238:241], v[162:165], v[26:29]
	v_mfma_f32_16x16x32_bf16 v[22:25], v[230:233], v[170:173], v[22:25]
	v_mfma_f32_16x16x32_bf16 v[18:21], v[238:241], v[170:173], v[18:21]
	v_mfma_f32_16x16x32_bf16 v[12:15], v[230:233], v[214:217], v[12:15]
	v_mfma_f32_16x16x32_bf16 v[8:11], v[238:241], v[214:217], v[8:11]
	v_mfma_f32_16x16x32_bf16 v[4:7], v[230:233], v[222:225], v[4:7]
	v_mfma_f32_16x16x32_bf16 v[0:3], v[238:241], v[222:225], v[0:3]
	s_barrier
	ds_read_b128 v[132:135], v148
	ds_read_b128 v[136:139], v148 offset:1024
	ds_read_b128 v[150:153], v148 offset:2048
	ds_read_b128 v[154:157], v148 offset:3072
	s_add_i32 s71, s69, 0x80100
	s_mov_b32 m0, s35
	ds_read_b128 v[158:161], v143 offset:32768
	ds_read_b128 v[162:165], v143 offset:33792
	ds_read_b128 v[166:169], v144 offset:32768
	ds_read_b128 v[170:173], v144 offset:33792
	ds_read_b128 v[178:181], v145 offset:32768
	ds_read_b128 v[214:217], v145 offset:33792
	ds_read_b128 v[218:221], v146 offset:32768
	ds_read_b128 v[222:225], v146 offset:33792
	buffer_load_dwordx4 v140, s[48:51], s71 offen lds
	s_mov_b32 m0, s36
	s_nop 0
	buffer_load_dwordx4 v141, s[48:51], s71 offen lds
	s_waitcnt lgkmcnt(8)
	s_barrier
	s_waitcnt lgkmcnt(0)
	s_waitcnt lgkmcnt(0)
	v_mfma_f32_16x16x32_bf16 v[126:129], v[132:135], v[158:161], v[126:129]
	v_mfma_f32_16x16x32_bf16 v[122:125], v[150:153], v[158:161], v[122:125]
	v_mfma_f32_16x16x32_bf16 v[118:121], v[132:135], v[166:169], v[118:121]
	v_mfma_f32_16x16x32_bf16 v[114:117], v[150:153], v[166:169], v[114:117]
	v_mfma_f32_16x16x32_bf16 v[110:113], v[132:135], v[178:181], v[110:113]
	v_mfma_f32_16x16x32_bf16 v[106:109], v[150:153], v[178:181], v[106:109]
	v_mfma_f32_16x16x32_bf16 v[102:105], v[132:135], v[218:221], v[102:105]
	v_mfma_f32_16x16x32_bf16 v[98:101], v[150:153], v[218:221], v[98:101]
	v_mfma_f32_16x16x32_bf16 v[126:129], v[136:139], v[162:165], v[126:129]
	v_mfma_f32_16x16x32_bf16 v[122:125], v[154:157], v[162:165], v[122:125]
	v_mfma_f32_16x16x32_bf16 v[118:121], v[136:139], v[170:173], v[118:121]
	v_mfma_f32_16x16x32_bf16 v[114:117], v[154:157], v[170:173], v[114:117]
	v_mfma_f32_16x16x32_bf16 v[110:113], v[136:139], v[214:217], v[110:113]
	v_mfma_f32_16x16x32_bf16 v[106:109], v[154:157], v[214:217], v[106:109]
	v_mfma_f32_16x16x32_bf16 v[102:105], v[136:139], v[222:225], v[102:105]
	v_mfma_f32_16x16x32_bf16 v[98:101], v[154:157], v[222:225], v[98:101]
	s_barrier
	s_add_i32 s71, s70, 0x180
	s_mov_b32 m0, s37
	ds_read_b128 v[226:229], v149
	ds_read_b128 v[230:233], v149 offset:1024
	ds_read_b128 v[234:237], v149 offset:2048
	ds_read_b128 v[238:241], v149 offset:3072
	buffer_load_dwordx4 v140, s[44:47], s71 offen lds
	s_mov_b32 m0, s38
	s_nop 0
	buffer_load_dwordx4 v141, s[44:47], s71 offen lds
	s_barrier
	s_waitcnt lgkmcnt(0)
	s_waitcnt lgkmcnt(0)
	v_mfma_f32_16x16x32_bf16 v[94:97], v[226:229], v[158:161], v[94:97]
	v_mfma_f32_16x16x32_bf16 v[90:93], v[234:237], v[158:161], v[90:93]
	v_mfma_f32_16x16x32_bf16 v[86:89], v[226:229], v[166:169], v[86:89]
	v_mfma_f32_16x16x32_bf16 v[82:85], v[234:237], v[166:169], v[82:85]
	v_mfma_f32_16x16x32_bf16 v[78:81], v[226:229], v[178:181], v[78:81]
	v_mfma_f32_16x16x32_bf16 v[74:77], v[234:237], v[178:181], v[74:77]
	v_mfma_f32_16x16x32_bf16 v[70:73], v[226:229], v[218:221], v[70:73]
	v_mfma_f32_16x16x32_bf16 v[66:69], v[234:237], v[218:221], v[66:69]
	v_mfma_f32_16x16x32_bf16 v[94:97], v[230:233], v[162:165], v[94:97]
	v_mfma_f32_16x16x32_bf16 v[90:93], v[238:241], v[162:165], v[90:93]
	v_mfma_f32_16x16x32_bf16 v[86:89], v[230:233], v[170:173], v[86:89]
	v_mfma_f32_16x16x32_bf16 v[82:85], v[238:241], v[170:173], v[82:85]
	v_mfma_f32_16x16x32_bf16 v[78:81], v[230:233], v[214:217], v[78:81]
	v_mfma_f32_16x16x32_bf16 v[74:77], v[238:241], v[214:217], v[74:77]
	v_mfma_f32_16x16x32_bf16 v[70:73], v[230:233], v[222:225], v[70:73]
	v_mfma_f32_16x16x32_bf16 v[66:69], v[238:241], v[222:225], v[66:69]
	s_addk_i32 s69, 0x180
	s_mov_b32 m0, s39
	s_barrier
	ds_read_b128 v[158:161], v143 offset:49152
	ds_read_b128 v[162:165], v143 offset:50176
	ds_read_b128 v[166:169], v144 offset:49152
	ds_read_b128 v[170:173], v144 offset:50176
	ds_read_b128 v[178:181], v145 offset:49152
	ds_read_b128 v[214:217], v145 offset:50176
	ds_read_b128 v[218:221], v146 offset:49152
	ds_read_b128 v[222:225], v146 offset:50176
	buffer_load_dwordx4 v140, s[48:51], s69 offen lds
	s_mov_b32 m0, s62
	s_nop 0
	buffer_load_dwordx4 v141, s[48:51], s69 offen lds
	s_barrier
	s_waitcnt lgkmcnt(0)
	s_waitcnt lgkmcnt(0)
	v_mfma_f32_16x16x32_bf16 v[62:65], v[132:135], v[158:161], v[62:65]
	v_mfma_f32_16x16x32_bf16 v[58:61], v[150:153], v[158:161], v[58:61]
	v_mfma_f32_16x16x32_bf16 v[54:57], v[132:135], v[166:169], v[54:57]
	v_mfma_f32_16x16x32_bf16 v[50:53], v[150:153], v[166:169], v[50:53]
	v_mfma_f32_16x16x32_bf16 v[46:49], v[132:135], v[178:181], v[46:49]
	v_mfma_f32_16x16x32_bf16 v[42:45], v[150:153], v[178:181], v[42:45]
	v_mfma_f32_16x16x32_bf16 v[38:41], v[132:135], v[218:221], v[38:41]
	v_mfma_f32_16x16x32_bf16 v[34:37], v[150:153], v[218:221], v[34:37]
	v_mfma_f32_16x16x32_bf16 v[62:65], v[136:139], v[162:165], v[62:65]
	v_mfma_f32_16x16x32_bf16 v[58:61], v[154:157], v[162:165], v[58:61]
	v_mfma_f32_16x16x32_bf16 v[54:57], v[136:139], v[170:173], v[54:57]
	v_mfma_f32_16x16x32_bf16 v[50:53], v[154:157], v[170:173], v[50:53]
	v_mfma_f32_16x16x32_bf16 v[46:49], v[136:139], v[214:217], v[46:49]
	v_mfma_f32_16x16x32_bf16 v[42:45], v[154:157], v[214:217], v[42:45]
	v_mfma_f32_16x16x32_bf16 v[38:41], v[136:139], v[222:225], v[38:41]
	v_mfma_f32_16x16x32_bf16 v[34:37], v[154:157], v[222:225], v[34:37]
	s_barrier
	s_add_i32 s70, s70, 0x80180
	s_mov_b32 m0, s63
	s_nop 0
	buffer_load_dwordx4 v140, s[44:47], s70 offen lds
	s_mov_b32 m0, s66
	s_nop 0
	buffer_load_dwordx4 v141, s[44:47], s70 offen lds
	s_waitcnt vmcnt(6)
	s_barrier
	v_mfma_f32_16x16x32_bf16 v[30:33], v[226:229], v[158:161], v[30:33]
	v_mfma_f32_16x16x32_bf16 v[26:29], v[234:237], v[158:161], v[26:29]
	v_mfma_f32_16x16x32_bf16 v[22:25], v[226:229], v[166:169], v[22:25]
	v_mfma_f32_16x16x32_bf16 v[18:21], v[234:237], v[166:169], v[18:21]
	v_mfma_f32_16x16x32_bf16 v[12:15], v[226:229], v[178:181], v[12:15]
	v_mfma_f32_16x16x32_bf16 v[8:11], v[234:237], v[178:181], v[8:11]
	v_mfma_f32_16x16x32_bf16 v[4:7], v[226:229], v[218:221], v[4:7]
	v_mfma_f32_16x16x32_bf16 v[0:3], v[234:237], v[218:221], v[0:3]
	v_mfma_f32_16x16x32_bf16 v[30:33], v[230:233], v[162:165], v[30:33]
	v_mfma_f32_16x16x32_bf16 v[26:29], v[238:241], v[162:165], v[26:29]
	v_mfma_f32_16x16x32_bf16 v[22:25], v[230:233], v[170:173], v[22:25]
	v_mfma_f32_16x16x32_bf16 v[18:21], v[238:241], v[170:173], v[18:21]
	v_mfma_f32_16x16x32_bf16 v[12:15], v[230:233], v[214:217], v[12:15]
	v_mfma_f32_16x16x32_bf16 v[8:11], v[238:241], v[214:217], v[8:11]
	v_mfma_f32_16x16x32_bf16 v[4:7], v[230:233], v[222:225], v[4:7]
	v_mfma_f32_16x16x32_bf16 v[0:3], v[238:241], v[222:225], v[0:3]
	s_add_i32 s67, s67, 2
	s_addk_i32 s68, 0x100
	s_cmp_lt_u32 s67, 28
	s_barrier
	s_cbranch_scc1 .LBB0_225
	v_mov_b32_e32 v150, v130
	s_or_b32 s8, s8, 0x80f80
	v_and_b32_e32 v158, 15, v150
	v_bfe_u32 v132, v150, 4, 2
	v_lshlrev_b32_e32 v134, 2, v150
	v_bfe_u32 v152, v150, 6, 2
	v_lshlrev_b32_e32 v151, 4, v132
	v_lshlrev_b32_e32 v133, 6, v158
	v_and_b32_e32 v139, 32, v134
	v_lshlrev_b32_e32 v138, 12, v152
	v_bitop3_b32 v153, v151, v139, v133 bitop3:0x36
	v_add3_u32 v133, s78, v153, v138
	ds_read_b128 v[134:137], v133
	ds_read_b128 v[154:157], v133 offset:1024
	ds_read_b128 v[160:163], v133 offset:2048
	ds_read_b128 v[164:167], v133 offset:3072
	v_ashrrev_i32_e32 v133, 2, v150
	v_lshlrev_b32_e32 v172, 6, v150
	v_and_b32_e32 v133, 0xffffffc0, v133
	v_and_b32_e32 v172, 0x3c0, v172
	v_lshlrev_b32_e32 v159, 7, v133
	v_bitop3_b32 v139, v172, v139, v151 bitop3:0x36
	s_waitcnt vmcnt(0)
	v_add3_u32 v176, 0, v153, v159
	v_add3_u32 v139, 0, v139, v159
	s_mov_b32 m0, s7
	ds_read_b128 v[168:171], v176
	ds_read_b128 v[178:181], v176 offset:1024
	ds_read_b128 v[214:217], v139 offset:2048
	ds_read_b128 v[218:221], v139 offset:3072
	ds_read_b128 v[222:225], v139 offset:4096
	ds_read_b128 v[226:229], v139 offset:5120
	ds_read_b128 v[230:233], v139 offset:6144
	ds_read_b128 v[234:237], v139 offset:7168
	buffer_load_dwordx4 v140, s[48:51], s8 offen lds
	s_mov_b32 m0, s6
	s_nop 0
	buffer_load_dwordx4 v141, s[48:51], s8 offen lds
	s_barrier
	s_waitcnt lgkmcnt(0)
	s_waitcnt lgkmcnt(0)
	v_mfma_f32_16x16x32_bf16 v[126:129], v[134:137], v[168:171], v[126:129]
	v_mfma_f32_16x16x32_bf16 v[122:125], v[160:163], v[168:171], v[122:125]
	v_mfma_f32_16x16x32_bf16 v[118:121], v[134:137], v[214:217], v[118:121]
	v_mfma_f32_16x16x32_bf16 v[114:117], v[160:163], v[214:217], v[114:117]
	v_mfma_f32_16x16x32_bf16 v[110:113], v[134:137], v[222:225], v[110:113]
	v_mfma_f32_16x16x32_bf16 v[106:109], v[160:163], v[222:225], v[106:109]
	v_mfma_f32_16x16x32_bf16 v[102:105], v[134:137], v[230:233], v[102:105]
	v_mfma_f32_16x16x32_bf16 v[98:101], v[160:163], v[230:233], v[98:101]
	v_mfma_f32_16x16x32_bf16 v[126:129], v[154:157], v[178:181], v[126:129]
	v_mfma_f32_16x16x32_bf16 v[122:125], v[164:167], v[178:181], v[122:125]
	v_mfma_f32_16x16x32_bf16 v[118:121], v[154:157], v[218:221], v[118:121]
	v_mfma_f32_16x16x32_bf16 v[114:117], v[164:167], v[218:221], v[114:117]
	v_mfma_f32_16x16x32_bf16 v[110:113], v[154:157], v[226:229], v[110:113]
	v_mfma_f32_16x16x32_bf16 v[106:109], v[164:167], v[226:229], v[106:109]
	v_mfma_f32_16x16x32_bf16 v[102:105], v[154:157], v[234:237], v[102:105]
	v_mfma_f32_16x16x32_bf16 v[98:101], v[164:167], v[234:237], v[98:101]
	v_add3_u32 v159, s77, v153, v138
	s_barrier
	ds_read_b128 v[238:241], v159
	ds_read_b128 v[242:245], v159 offset:1024
	ds_read_b128 v[246:249], v159 offset:2048
	ds_read_b128 v[250:253], v159 offset:3072
	s_barrier
	s_waitcnt lgkmcnt(0)
	s_waitcnt lgkmcnt(0)
	v_mfma_f32_16x16x32_bf16 v[94:97], v[238:241], v[168:171], v[94:97]
	v_mfma_f32_16x16x32_bf16 v[182:185], v[242:245], v[178:181], v[94:97]
	v_mfma_f32_16x16x32_bf16 v[90:93], v[246:249], v[168:171], v[90:93]
	v_mfma_f32_16x16x32_bf16 v[86:89], v[238:241], v[214:217], v[86:89]
	v_mfma_f32_16x16x32_bf16 v[82:85], v[246:249], v[214:217], v[82:85]
	v_mfma_f32_16x16x32_bf16 v[78:81], v[238:241], v[222:225], v[78:81]
	v_mfma_f32_16x16x32_bf16 v[74:77], v[246:249], v[222:225], v[74:77]
	v_mfma_f32_16x16x32_bf16 v[70:73], v[238:241], v[230:233], v[70:73]
	v_mfma_f32_16x16x32_bf16 v[66:69], v[246:249], v[230:233], v[66:69]
	v_mfma_f32_16x16x32_bf16 v[168:171], v[250:253], v[178:181], v[90:93]
	v_mfma_f32_16x16x32_bf16 v[178:181], v[242:245], v[218:221], v[86:89]
	v_mfma_f32_16x16x32_bf16 v[214:217], v[250:253], v[218:221], v[82:85]
	v_mfma_f32_16x16x32_bf16 v[218:221], v[242:245], v[226:229], v[78:81]
	v_mfma_f32_16x16x32_bf16 v[222:225], v[250:253], v[226:229], v[74:77]
	v_mfma_f32_16x16x32_bf16 v[226:229], v[242:245], v[234:237], v[70:73]
	v_mfma_f32_16x16x32_bf16 v[230:233], v[250:253], v[234:237], v[66:69]
	s_barrier
	s_nop 0
	ds_read_b128 v[66:69], v176 offset:16384
	ds_read_b128 v[70:73], v176 offset:17408
	ds_read_b128 v[74:77], v139 offset:18432
	ds_read_b128 v[78:81], v139 offset:19456
	ds_read_b128 v[82:85], v139 offset:20480
	ds_read_b128 v[86:89], v139 offset:21504
	ds_read_b128 v[90:93], v139 offset:22528
	ds_read_b128 v[94:97], v139 offset:23552
	s_waitcnt vmcnt(4)
	s_barrier
	s_waitcnt lgkmcnt(0)
	s_waitcnt lgkmcnt(0)
	v_mfma_f32_16x16x32_bf16 v[62:65], v[134:137], v[66:69], v[62:65]
	v_mfma_f32_16x16x32_bf16 v[58:61], v[160:163], v[66:69], v[58:61]
	v_mfma_f32_16x16x32_bf16 v[54:57], v[134:137], v[74:77], v[54:57]
	v_mfma_f32_16x16x32_bf16 v[50:53], v[160:163], v[74:77], v[50:53]
	v_mfma_f32_16x16x32_bf16 v[46:49], v[134:137], v[82:85], v[46:49]
	v_mfma_f32_16x16x32_bf16 v[42:45], v[160:163], v[82:85], v[42:45]
	v_mfma_f32_16x16x32_bf16 v[38:41], v[134:137], v[90:93], v[38:41]
	v_mfma_f32_16x16x32_bf16 v[34:37], v[160:163], v[90:93], v[34:37]
	v_mfma_f32_16x16x32_bf16 v[62:65], v[154:157], v[70:73], v[62:65]
	v_mfma_f32_16x16x32_bf16 v[58:61], v[164:167], v[70:73], v[58:61]
	v_mfma_f32_16x16x32_bf16 v[54:57], v[154:157], v[78:81], v[54:57]
	v_mfma_f32_16x16x32_bf16 v[50:53], v[164:167], v[78:81], v[50:53]
	v_mfma_f32_16x16x32_bf16 v[46:49], v[154:157], v[86:89], v[46:49]
	v_mfma_f32_16x16x32_bf16 v[42:45], v[164:167], v[86:89], v[42:45]
	v_mfma_f32_16x16x32_bf16 v[38:41], v[154:157], v[94:97], v[38:41]
	v_mfma_f32_16x16x32_bf16 v[34:37], v[164:167], v[94:97], v[34:37]
	v_mfma_f32_16x16x32_bf16 v[30:33], v[238:241], v[66:69], v[30:33]
	v_mfma_f32_16x16x32_bf16 v[26:29], v[246:249], v[66:69], v[26:29]
	v_mfma_f32_16x16x32_bf16 v[22:25], v[238:241], v[74:77], v[22:25]
	v_mfma_f32_16x16x32_bf16 v[18:21], v[246:249], v[74:77], v[18:21]
	v_mfma_f32_16x16x32_bf16 v[12:15], v[238:241], v[82:85], v[12:15]
	v_mfma_f32_16x16x32_bf16 v[8:11], v[246:249], v[82:85], v[8:11]
	v_mfma_f32_16x16x32_bf16 v[4:7], v[238:241], v[90:93], v[4:7]
	v_mfma_f32_16x16x32_bf16 v[0:3], v[246:249], v[90:93], v[0:3]
	v_mfma_f32_16x16x32_bf16 v[134:137], v[242:245], v[70:73], v[30:33]
	v_mfma_f32_16x16x32_bf16 v[154:157], v[250:253], v[70:73], v[26:29]
	v_mfma_f32_16x16x32_bf16 v[160:163], v[242:245], v[78:81], v[22:25]
	v_mfma_f32_16x16x32_bf16 v[164:167], v[250:253], v[78:81], v[18:21]
	v_mfma_f32_16x16x32_bf16 v[234:237], v[242:245], v[86:89], v[12:15]
	v_mfma_f32_16x16x32_bf16 v[82:85], v[250:253], v[86:89], v[8:11]
	v_mfma_f32_16x16x32_bf16 v[238:241], v[242:245], v[94:97], v[4:7]
	v_mfma_f32_16x16x32_bf16 v[242:245], v[250:253], v[94:97], v[0:3]
	s_nop 1
	v_add3_u32 v0, s2, v153, v138
	s_barrier
	ds_read_b128 v[246:249], v0
	ds_read_b128 v[250:253], v0 offset:1024
	ds_read_b128 v[200:203], v0 offset:2048
	ds_read_b128 v[172:175], v0 offset:3072
	ds_read_b128 v[4:7], v176 offset:32768
	ds_read_b128 v[8:11], v176 offset:33792
	ds_read_b128 v[12:15], v139 offset:34816
	ds_read_b128 v[18:21], v139 offset:35840
	ds_read_b128 v[22:25], v139 offset:36864
	ds_read_b128 v[26:29], v139 offset:37888
	ds_read_b128 v[30:33], v139 offset:38912
	ds_read_b128 v[208:211], v139 offset:39936
	s_waitcnt vmcnt(2)
	s_barrier
	s_waitcnt lgkmcnt(0)
	s_waitcnt lgkmcnt(0)
	v_mfma_f32_16x16x32_bf16 v[0:3], v[246:249], v[4:7], v[126:129]
	v_mfma_f32_16x16x32_bf16 v[126:129], v[250:253], v[8:11], v[0:3]
	v_mfma_f32_16x16x32_bf16 v[0:3], v[200:203], v[4:7], v[122:125]
	v_mfma_f32_16x16x32_bf16 v[122:125], v[172:175], v[8:11], v[0:3]
	v_mfma_f32_16x16x32_bf16 v[0:3], v[246:249], v[12:15], v[118:121]
	v_mfma_f32_16x16x32_bf16 v[90:93], v[250:253], v[18:21], v[0:3]
	v_mfma_f32_16x16x32_bf16 v[0:3], v[200:203], v[12:15], v[114:117]
	v_mfma_f32_16x16x32_bf16 v[94:97], v[172:175], v[18:21], v[0:3]
	v_mfma_f32_16x16x32_bf16 v[0:3], v[246:249], v[22:25], v[110:113]
	v_mfma_f32_16x16x32_bf16 v[74:77], v[250:253], v[26:29], v[0:3]
	v_mfma_f32_16x16x32_bf16 v[0:3], v[200:203], v[22:25], v[106:109]
	v_mfma_f32_16x16x32_bf16 v[86:89], v[172:175], v[26:29], v[0:3]
	v_mfma_f32_16x16x32_bf16 v[0:3], v[246:249], v[30:33], v[102:105]
	v_mfma_f32_16x16x32_bf16 v[196:199], v[250:253], v[208:211], v[0:3]
	v_mfma_f32_16x16x32_bf16 v[0:3], v[200:203], v[30:33], v[98:101]
	v_mfma_f32_16x16x32_bf16 v[78:81], v[172:175], v[208:211], v[0:3]
	v_add3_u32 v70, s91, v153, v138
	s_barrier
	ds_read_b128 v[204:207], v70
	s_nop 2
	ds_read_b128 v[0:3], v70 offset:1024
	ds_read_b128 v[66:69], v70 offset:2048
	ds_read_b128 v[70:73], v70 offset:3072
	s_waitcnt vmcnt(0)
	s_barrier
	s_waitcnt lgkmcnt(0)
	s_waitcnt lgkmcnt(0)
	v_mfma_f32_16x16x32_bf16 v[98:101], v[204:207], v[4:7], v[182:185]
	v_mfma_f32_16x16x32_bf16 v[4:7], v[66:69], v[4:7], v[168:171]
	v_mfma_f32_16x16x32_bf16 v[98:101], v[0:3], v[8:11], v[98:101]
	v_mfma_f32_16x16x32_bf16 v[102:105], v[70:73], v[8:11], v[4:7]
	v_mfma_f32_16x16x32_bf16 v[8:11], v[204:207], v[12:15], v[178:181]
	v_mfma_f32_16x16x32_bf16 v[12:15], v[66:69], v[12:15], v[214:217]
	v_mfma_f32_16x16x32_bf16 v[8:11], v[0:3], v[18:21], v[8:11]
	v_mfma_f32_16x16x32_bf16 v[12:15], v[70:73], v[18:21], v[12:15]
	v_mfma_f32_16x16x32_bf16 v[18:21], v[204:207], v[22:25], v[218:221]
	v_mfma_f32_16x16x32_bf16 v[22:25], v[66:69], v[22:25], v[222:225]
	v_mfma_f32_16x16x32_bf16 v[18:21], v[0:3], v[26:29], v[18:21]
	v_mfma_f32_16x16x32_bf16 v[22:25], v[70:73], v[26:29], v[22:25]
	v_mfma_f32_16x16x32_bf16 v[26:29], v[204:207], v[30:33], v[226:229]
	v_mfma_f32_16x16x32_bf16 v[30:33], v[66:69], v[30:33], v[230:233]
	v_mfma_f32_16x16x32_bf16 v[26:29], v[0:3], v[208:211], v[26:29]
	v_mfma_f32_16x16x32_bf16 v[30:33], v[70:73], v[208:211], v[30:33]
	s_barrier
	ds_read_b128 v[168:171], v176 offset:49152
	ds_read_b128 v[178:181], v176 offset:50176
	ds_read_b128 v[208:211], v139 offset:51200
	ds_read_b128 v[214:217], v139 offset:52224
	ds_read_b128 v[218:221], v139 offset:53248
	ds_read_b128 v[222:225], v139 offset:54272
	ds_read_b128 v[226:229], v139 offset:55296
	ds_read_b128 v[230:233], v139 offset:56320
	s_barrier
	s_waitcnt lgkmcnt(0)
	s_waitcnt lgkmcnt(0)
	v_mfma_f32_16x16x32_bf16 v[62:65], v[246:249], v[168:171], v[62:65]
	v_mfma_f32_16x16x32_bf16 v[58:61], v[200:203], v[168:171], v[58:61]
	v_mfma_f32_16x16x32_bf16 v[54:57], v[246:249], v[208:211], v[54:57]
	v_mfma_f32_16x16x32_bf16 v[50:53], v[200:203], v[208:211], v[50:53]
	v_mfma_f32_16x16x32_bf16 v[46:49], v[246:249], v[218:221], v[46:49]
	v_mfma_f32_16x16x32_bf16 v[42:45], v[200:203], v[218:221], v[42:45]
	v_mfma_f32_16x16x32_bf16 v[38:41], v[246:249], v[226:229], v[38:41]
	v_mfma_f32_16x16x32_bf16 v[34:37], v[200:203], v[226:229], v[34:37]
	v_mfma_f32_16x16x32_bf16 v[4:7], v[250:253], v[178:181], v[62:65]
	v_mfma_f32_16x16x32_bf16 v[182:185], v[172:175], v[178:181], v[58:61]
	v_mfma_f32_16x16x32_bf16 v[114:117], v[250:253], v[214:217], v[54:57]
	v_mfma_f32_16x16x32_bf16 v[118:121], v[172:175], v[214:217], v[50:53]
	v_mfma_f32_16x16x32_bf16 v[106:109], v[250:253], v[222:225], v[46:49]
	v_mfma_f32_16x16x32_bf16 v[110:113], v[172:175], v[222:225], v[42:45]
	v_mfma_f32_16x16x32_bf16 v[246:249], v[250:253], v[230:233], v[38:41]
	v_mfma_f32_16x16x32_bf16 v[250:253], v[172:175], v[230:233], v[34:37]
	v_mfma_f32_16x16x32_bf16 v[34:37], v[204:207], v[168:171], v[134:137]
	v_mfma_f32_16x16x32_bf16 v[42:45], v[204:207], v[208:211], v[160:163]
	v_mfma_f32_16x16x32_bf16 v[50:53], v[204:207], v[218:221], v[234:237]
	v_mfma_f32_16x16x32_bf16 v[58:61], v[204:207], v[226:229], v[238:241]
	v_mfma_f32_16x16x32_bf16 v[34:37], v[0:3], v[178:181], v[34:37]
	v_mfma_f32_16x16x32_bf16 v[38:41], v[66:69], v[168:171], v[154:157]
	v_mfma_f32_16x16x32_bf16 v[42:45], v[0:3], v[214:217], v[42:45]
	v_mfma_f32_16x16x32_bf16 v[46:49], v[66:69], v[208:211], v[164:167]
	v_mfma_f32_16x16x32_bf16 v[50:53], v[0:3], v[222:225], v[50:53]
	v_mfma_f32_16x16x32_bf16 v[54:57], v[66:69], v[218:221], v[82:85]
	v_mfma_f32_16x16x32_bf16 v[58:61], v[0:3], v[230:233], v[58:61]
	v_mfma_f32_16x16x32_bf16 v[0:3], v[66:69], v[226:229], v[242:245]
	v_mfma_f32_16x16x32_bf16 v[38:41], v[70:73], v[178:181], v[38:41]
	v_mfma_f32_16x16x32_bf16 v[46:49], v[70:73], v[214:217], v[46:49]
	v_mfma_f32_16x16x32_bf16 v[54:57], v[70:73], v[222:225], v[54:57]
	v_mfma_f32_16x16x32_bf16 v[62:65], v[70:73], v[230:233], v[0:3]
	s_setprio 0
	s_movk_i32 s0, 0x100
	v_cmp_gt_u32_e32 vcc, s0, v150
	s_barrier
	s_and_saveexec_b64 s[6:7], vcc
	s_cbranch_execz .LBB0_228
	s_barrier

.LBB0_526:
	ds_read_b128 v[144:147], v136
	ds_read_b128 v[148:151], v136 offset:1024
	ds_read_b128 v[152:155], v136 offset:2048
	ds_read_b128 v[156:159], v136 offset:3072
	s_add_i32 s35, s15, s34
	s_add_i32 s36, s35, 0x80080
	s_mov_b32 m0, s7
	ds_read_b128 v[160:163], v137
	ds_read_b128 v[164:167], v137 offset:1024
	ds_read_b128 v[168:171], v138
	ds_read_b128 v[172:175], v138 offset:1024
	ds_read_b128 v[178:181], v139
	ds_read_b128 v[182:185], v139 offset:1024
	ds_read_b128 v[196:199], v140
	ds_read_b128 v[200:203], v140 offset:1024
	buffer_load_dwordx4 v134, s[48:51], s36 offen lds
	s_mov_b32 m0, s6
	s_nop 0
	buffer_load_dwordx4 v135, s[48:51], s36 offen lds
	s_waitcnt lgkmcnt(8)
	s_barrier
	s_waitcnt lgkmcnt(0)
	s_waitcnt lgkmcnt(7)
	v_mfma_f32_16x16x32_bf16 v[126:129], v[144:147], v[160:163], v[126:129]
	v_mfma_f32_16x16x32_bf16 v[122:125], v[152:155], v[160:163], v[122:125]
	s_waitcnt lgkmcnt(5)
	v_mfma_f32_16x16x32_bf16 v[118:121], v[144:147], v[168:171], v[118:121]
	v_mfma_f32_16x16x32_bf16 v[114:117], v[152:155], v[168:171], v[114:117]
	s_waitcnt lgkmcnt(3)
	v_mfma_f32_16x16x32_bf16 v[110:113], v[144:147], v[178:181], v[110:113]
	v_mfma_f32_16x16x32_bf16 v[106:109], v[152:155], v[178:181], v[106:109]
	s_waitcnt lgkmcnt(1)
	v_mfma_f32_16x16x32_bf16 v[102:105], v[144:147], v[196:199], v[102:105]
	v_mfma_f32_16x16x32_bf16 v[98:101], v[152:155], v[196:199], v[98:101]
	v_mfma_f32_16x16x32_bf16 v[126:129], v[148:151], v[164:167], v[126:129]
	v_mfma_f32_16x16x32_bf16 v[122:125], v[156:159], v[164:167], v[122:125]
	v_mfma_f32_16x16x32_bf16 v[118:121], v[148:151], v[172:175], v[118:121]
	v_mfma_f32_16x16x32_bf16 v[114:117], v[156:159], v[172:175], v[114:117]
	v_mfma_f32_16x16x32_bf16 v[110:113], v[148:151], v[182:185], v[110:113]
	v_mfma_f32_16x16x32_bf16 v[106:109], v[156:159], v[182:185], v[106:109]
	s_waitcnt lgkmcnt(0)
	v_mfma_f32_16x16x32_bf16 v[102:105], v[148:151], v[200:203], v[102:105]
	v_mfma_f32_16x16x32_bf16 v[98:101], v[156:159], v[200:203], v[98:101]
	s_barrier
	s_add_i32 s36, s16, s34
	s_add_i32 s37, s36, 0x100
	s_mov_b32 m0, s18
	ds_read_b128 v[204:207], v141
	ds_read_b128 v[208:211], v141 offset:1024
	ds_read_b128 v[214:217], v141 offset:2048
	ds_read_b128 v[218:221], v141 offset:3072
	buffer_load_dwordx4 v134, s[52:55], s37 offen lds
	s_mov_b32 m0, s19
	s_nop 0
	buffer_load_dwordx4 v135, s[52:55], s37 offen lds
	s_barrier
	s_waitcnt lgkmcnt(0)
	s_waitcnt lgkmcnt(3)
	v_mfma_f32_16x16x32_bf16 v[94:97], v[204:207], v[160:163], v[94:97]
	s_waitcnt lgkmcnt(1)
	v_mfma_f32_16x16x32_bf16 v[90:93], v[214:217], v[160:163], v[90:93]
	v_mfma_f32_16x16x32_bf16 v[86:89], v[204:207], v[168:171], v[86:89]
	v_mfma_f32_16x16x32_bf16 v[82:85], v[214:217], v[168:171], v[82:85]
	v_mfma_f32_16x16x32_bf16 v[78:81], v[204:207], v[178:181], v[78:81]
	v_mfma_f32_16x16x32_bf16 v[74:77], v[214:217], v[178:181], v[74:77]
	v_mfma_f32_16x16x32_bf16 v[70:73], v[204:207], v[196:199], v[70:73]
	v_mfma_f32_16x16x32_bf16 v[66:69], v[214:217], v[196:199], v[66:69]
	v_mfma_f32_16x16x32_bf16 v[94:97], v[208:211], v[164:167], v[94:97]
	s_waitcnt lgkmcnt(0)
	v_mfma_f32_16x16x32_bf16 v[90:93], v[218:221], v[164:167], v[90:93]
	v_mfma_f32_16x16x32_bf16 v[86:89], v[208:211], v[172:175], v[86:89]
	v_mfma_f32_16x16x32_bf16 v[82:85], v[218:221], v[172:175], v[82:85]
	v_mfma_f32_16x16x32_bf16 v[78:81], v[208:211], v[182:185], v[78:81]
	v_mfma_f32_16x16x32_bf16 v[74:77], v[218:221], v[182:185], v[74:77]
	v_mfma_f32_16x16x32_bf16 v[70:73], v[208:211], v[200:203], v[70:73]
	v_mfma_f32_16x16x32_bf16 v[66:69], v[218:221], v[200:203], v[66:69]
	s_add_i32 s37, s35, 0x100
	s_mov_b32 m0, s17
	s_barrier
	ds_read_b128 v[160:163], v137 offset:16384
	ds_read_b128 v[164:167], v137 offset:17408
	ds_read_b128 v[168:171], v138 offset:16384
	ds_read_b128 v[172:175], v138 offset:17408
	ds_read_b128 v[178:181], v139 offset:16384
	ds_read_b128 v[182:185], v139 offset:17408
	ds_read_b128 v[196:199], v140 offset:16384
	ds_read_b128 v[200:203], v140 offset:17408
	buffer_load_dwordx4 v134, s[48:51], s37 offen lds
	s_mov_b32 m0, s20
	s_nop 0
	buffer_load_dwordx4 v135, s[48:51], s37 offen lds
	s_barrier
	s_waitcnt lgkmcnt(0)
	s_waitcnt lgkmcnt(7)
	v_mfma_f32_16x16x32_bf16 v[62:65], v[144:147], v[160:163], v[62:65]
	v_mfma_f32_16x16x32_bf16 v[58:61], v[152:155], v[160:163], v[58:61]
	s_waitcnt lgkmcnt(5)
	v_mfma_f32_16x16x32_bf16 v[54:57], v[144:147], v[168:171], v[54:57]
	v_mfma_f32_16x16x32_bf16 v[50:53], v[152:155], v[168:171], v[50:53]
	s_waitcnt lgkmcnt(3)
	v_mfma_f32_16x16x32_bf16 v[46:49], v[144:147], v[178:181], v[46:49]
	v_mfma_f32_16x16x32_bf16 v[42:45], v[152:155], v[178:181], v[42:45]
	s_waitcnt lgkmcnt(1)
	v_mfma_f32_16x16x32_bf16 v[38:41], v[144:147], v[196:199], v[38:41]
	v_mfma_f32_16x16x32_bf16 v[34:37], v[152:155], v[196:199], v[34:37]
	v_mfma_f32_16x16x32_bf16 v[62:65], v[148:151], v[164:167], v[62:65]
	v_mfma_f32_16x16x32_bf16 v[58:61], v[156:159], v[164:167], v[58:61]
	v_mfma_f32_16x16x32_bf16 v[54:57], v[148:151], v[172:175], v[54:57]
	v_mfma_f32_16x16x32_bf16 v[50:53], v[156:159], v[172:175], v[50:53]
	v_mfma_f32_16x16x32_bf16 v[46:49], v[148:151], v[182:185], v[46:49]
	v_mfma_f32_16x16x32_bf16 v[42:45], v[156:159], v[182:185], v[42:45]
	s_waitcnt lgkmcnt(0)
	v_mfma_f32_16x16x32_bf16 v[38:41], v[148:151], v[200:203], v[38:41]
	v_mfma_f32_16x16x32_bf16 v[34:37], v[156:159], v[200:203], v[34:37]
	s_barrier
	s_add_i32 s37, s36, 0x80100
	s_mov_b32 m0, s21
	s_nop 0
	buffer_load_dwordx4 v134, s[52:55], s37 offen lds
	s_mov_b32 m0, s22
	s_nop 0
	buffer_load_dwordx4 v135, s[52:55], s37 offen lds
	s_waitcnt vmcnt(6)
	s_barrier
	v_mfma_f32_16x16x32_bf16 v[30:33], v[204:207], v[160:163], v[30:33]
	v_mfma_f32_16x16x32_bf16 v[26:29], v[214:217], v[160:163], v[26:29]
	v_mfma_f32_16x16x32_bf16 v[22:25], v[204:207], v[168:171], v[22:25]
	v_mfma_f32_16x16x32_bf16 v[18:21], v[214:217], v[168:171], v[18:21]
	v_mfma_f32_16x16x32_bf16 v[12:15], v[204:207], v[178:181], v[12:15]
	v_mfma_f32_16x16x32_bf16 v[8:11], v[214:217], v[178:181], v[8:11]
	v_mfma_f32_16x16x32_bf16 v[4:7], v[204:207], v[196:199], v[4:7]
	v_mfma_f32_16x16x32_bf16 v[0:3], v[214:217], v[196:199], v[0:3]
	v_mfma_f32_16x16x32_bf16 v[30:33], v[208:211], v[164:167], v[30:33]
	v_mfma_f32_16x16x32_bf16 v[26:29], v[218:221], v[164:167], v[26:29]
	v_mfma_f32_16x16x32_bf16 v[22:25], v[208:211], v[172:175], v[22:25]
	v_mfma_f32_16x16x32_bf16 v[18:21], v[218:221], v[172:175], v[18:21]
	v_mfma_f32_16x16x32_bf16 v[12:15], v[208:211], v[182:185], v[12:15]
	v_mfma_f32_16x16x32_bf16 v[8:11], v[218:221], v[182:185], v[8:11]
	v_mfma_f32_16x16x32_bf16 v[4:7], v[208:211], v[200:203], v[4:7]
	v_mfma_f32_16x16x32_bf16 v[0:3], v[218:221], v[200:203], v[0:3]
	s_barrier
	ds_read_b128 v[144:147], v142
	ds_read_b128 v[148:151], v142 offset:1024
	ds_read_b128 v[152:155], v142 offset:2048
	ds_read_b128 v[156:159], v142 offset:3072
	s_add_i32 s37, s35, 0x80100
	s_mov_b32 m0, s23
	ds_read_b128 v[160:163], v137 offset:32768
	ds_read_b128 v[164:167], v137 offset:33792
	ds_read_b128 v[168:171], v138 offset:32768
	ds_read_b128 v[172:175], v138 offset:33792
	ds_read_b128 v[178:181], v139 offset:32768
	ds_read_b128 v[182:185], v139 offset:33792
	ds_read_b128 v[196:199], v140 offset:32768
	ds_read_b128 v[200:203], v140 offset:33792
	buffer_load_dwordx4 v134, s[48:51], s37 offen lds
	s_mov_b32 m0, s24
	s_nop 0
	buffer_load_dwordx4 v135, s[48:51], s37 offen lds
	s_waitcnt lgkmcnt(8)
	s_barrier
	s_waitcnt lgkmcnt(0)
	s_waitcnt lgkmcnt(7)
	v_mfma_f32_16x16x32_bf16 v[126:129], v[144:147], v[160:163], v[126:129]
	v_mfma_f32_16x16x32_bf16 v[122:125], v[152:155], v[160:163], v[122:125]
	s_waitcnt lgkmcnt(5)
	v_mfma_f32_16x16x32_bf16 v[118:121], v[144:147], v[168:171], v[118:121]
	v_mfma_f32_16x16x32_bf16 v[114:117], v[152:155], v[168:171], v[114:117]
	s_waitcnt lgkmcnt(3)
	v_mfma_f32_16x16x32_bf16 v[110:113], v[144:147], v[178:181], v[110:113]
	v_mfma_f32_16x16x32_bf16 v[106:109], v[152:155], v[178:181], v[106:109]
	s_waitcnt lgkmcnt(1)
	v_mfma_f32_16x16x32_bf16 v[102:105], v[144:147], v[196:199], v[102:105]
	v_mfma_f32_16x16x32_bf16 v[98:101], v[152:155], v[196:199], v[98:101]
	v_mfma_f32_16x16x32_bf16 v[126:129], v[148:151], v[164:167], v[126:129]
	v_mfma_f32_16x16x32_bf16 v[122:125], v[156:159], v[164:167], v[122:125]
	v_mfma_f32_16x16x32_bf16 v[118:121], v[148:151], v[172:175], v[118:121]
	v_mfma_f32_16x16x32_bf16 v[114:117], v[156:159], v[172:175], v[114:117]
	v_mfma_f32_16x16x32_bf16 v[110:113], v[148:151], v[182:185], v[110:113]
	v_mfma_f32_16x16x32_bf16 v[106:109], v[156:159], v[182:185], v[106:109]
	s_waitcnt lgkmcnt(0)
	v_mfma_f32_16x16x32_bf16 v[102:105], v[148:151], v[200:203], v[102:105]
	v_mfma_f32_16x16x32_bf16 v[98:101], v[156:159], v[200:203], v[98:101]
	s_barrier
	s_add_i32 s37, s36, 0x180
	s_mov_b32 m0, s25
	ds_read_b128 v[204:207], v143
	ds_read_b128 v[208:211], v143 offset:1024
	ds_read_b128 v[214:217], v143 offset:2048
	ds_read_b128 v[218:221], v143 offset:3072
	buffer_load_dwordx4 v134, s[52:55], s37 offen lds
	s_mov_b32 m0, s26
	s_nop 0
	buffer_load_dwordx4 v135, s[52:55], s37 offen lds
	s_barrier
	s_waitcnt lgkmcnt(0)
	s_waitcnt lgkmcnt(3)
	v_mfma_f32_16x16x32_bf16 v[94:97], v[204:207], v[160:163], v[94:97]
	s_waitcnt lgkmcnt(1)
	v_mfma_f32_16x16x32_bf16 v[90:93], v[214:217], v[160:163], v[90:93]
	v_mfma_f32_16x16x32_bf16 v[86:89], v[204:207], v[168:171], v[86:89]
	v_mfma_f32_16x16x32_bf16 v[82:85], v[214:217], v[168:171], v[82:85]
	v_mfma_f32_16x16x32_bf16 v[78:81], v[204:207], v[178:181], v[78:81]
	v_mfma_f32_16x16x32_bf16 v[74:77], v[214:217], v[178:181], v[74:77]
	v_mfma_f32_16x16x32_bf16 v[70:73], v[204:207], v[196:199], v[70:73]
	v_mfma_f32_16x16x32_bf16 v[66:69], v[214:217], v[196:199], v[66:69]
	v_mfma_f32_16x16x32_bf16 v[94:97], v[208:211], v[164:167], v[94:97]
	s_waitcnt lgkmcnt(0)
	v_mfma_f32_16x16x32_bf16 v[90:93], v[218:221], v[164:167], v[90:93]
	v_mfma_f32_16x16x32_bf16 v[86:89], v[208:211], v[172:175], v[86:89]
	v_mfma_f32_16x16x32_bf16 v[82:85], v[218:221], v[172:175], v[82:85]
	v_mfma_f32_16x16x32_bf16 v[78:81], v[208:211], v[182:185], v[78:81]
	v_mfma_f32_16x16x32_bf16 v[74:77], v[218:221], v[182:185], v[74:77]
	v_mfma_f32_16x16x32_bf16 v[70:73], v[208:211], v[200:203], v[70:73]
	v_mfma_f32_16x16x32_bf16 v[66:69], v[218:221], v[200:203], v[66:69]
	s_addk_i32 s35, 0x180
	s_mov_b32 m0, s27
	s_barrier
	ds_read_b128 v[160:163], v137 offset:49152
	ds_read_b128 v[164:167], v137 offset:50176
	ds_read_b128 v[168:171], v138 offset:49152
	ds_read_b128 v[172:175], v138 offset:50176
	ds_read_b128 v[178:181], v139 offset:49152
	ds_read_b128 v[182:185], v139 offset:50176
	ds_read_b128 v[196:199], v140 offset:49152
	ds_read_b128 v[200:203], v140 offset:50176
	buffer_load_dwordx4 v134, s[48:51], s35 offen lds
	s_mov_b32 m0, s28
	s_nop 0
	buffer_load_dwordx4 v135, s[48:51], s35 offen lds
	s_barrier
	s_waitcnt lgkmcnt(0)
	s_waitcnt lgkmcnt(7)
	v_mfma_f32_16x16x32_bf16 v[62:65], v[144:147], v[160:163], v[62:65]
	v_mfma_f32_16x16x32_bf16 v[58:61], v[152:155], v[160:163], v[58:61]
	s_waitcnt lgkmcnt(5)
	v_mfma_f32_16x16x32_bf16 v[54:57], v[144:147], v[168:171], v[54:57]
	v_mfma_f32_16x16x32_bf16 v[50:53], v[152:155], v[168:171], v[50:53]
	s_waitcnt lgkmcnt(3)
	v_mfma_f32_16x16x32_bf16 v[46:49], v[144:147], v[178:181], v[46:49]
	v_mfma_f32_16x16x32_bf16 v[42:45], v[152:155], v[178:181], v[42:45]
	s_waitcnt lgkmcnt(1)
	v_mfma_f32_16x16x32_bf16 v[38:41], v[144:147], v[196:199], v[38:41]
	v_mfma_f32_16x16x32_bf16 v[34:37], v[152:155], v[196:199], v[34:37]
	v_mfma_f32_16x16x32_bf16 v[62:65], v[148:151], v[164:167], v[62:65]
	v_mfma_f32_16x16x32_bf16 v[58:61], v[156:159], v[164:167], v[58:61]
	v_mfma_f32_16x16x32_bf16 v[54:57], v[148:151], v[172:175], v[54:57]
	v_mfma_f32_16x16x32_bf16 v[50:53], v[156:159], v[172:175], v[50:53]
	v_mfma_f32_16x16x32_bf16 v[46:49], v[148:151], v[182:185], v[46:49]
	v_mfma_f32_16x16x32_bf16 v[42:45], v[156:159], v[182:185], v[42:45]
	s_waitcnt lgkmcnt(0)
	v_mfma_f32_16x16x32_bf16 v[38:41], v[148:151], v[200:203], v[38:41]
	v_mfma_f32_16x16x32_bf16 v[34:37], v[156:159], v[200:203], v[34:37]
	s_barrier
	s_add_i32 s36, s36, 0x80180
	s_mov_b32 m0, s29
	s_nop 0
	buffer_load_dwordx4 v134, s[52:55], s36 offen lds
	s_mov_b32 m0, s30
	s_nop 0
	buffer_load_dwordx4 v135, s[52:55], s36 offen lds
	s_waitcnt vmcnt(6)
	s_barrier
	v_mfma_f32_16x16x32_bf16 v[30:33], v[204:207], v[160:163], v[30:33]
	v_mfma_f32_16x16x32_bf16 v[26:29], v[214:217], v[160:163], v[26:29]
	v_mfma_f32_16x16x32_bf16 v[22:25], v[204:207], v[168:171], v[22:25]
	v_mfma_f32_16x16x32_bf16 v[18:21], v[214:217], v[168:171], v[18:21]
	v_mfma_f32_16x16x32_bf16 v[12:15], v[204:207], v[178:181], v[12:15]
	v_mfma_f32_16x16x32_bf16 v[8:11], v[214:217], v[178:181], v[8:11]
	v_mfma_f32_16x16x32_bf16 v[4:7], v[204:207], v[196:199], v[4:7]
	v_mfma_f32_16x16x32_bf16 v[0:3], v[214:217], v[196:199], v[0:3]
	v_mfma_f32_16x16x32_bf16 v[30:33], v[208:211], v[164:167], v[30:33]
	v_mfma_f32_16x16x32_bf16 v[26:29], v[218:221], v[164:167], v[26:29]
	v_mfma_f32_16x16x32_bf16 v[22:25], v[208:211], v[172:175], v[22:25]
	v_mfma_f32_16x16x32_bf16 v[18:21], v[218:221], v[172:175], v[18:21]
	v_mfma_f32_16x16x32_bf16 v[12:15], v[208:211], v[182:185], v[12:15]
	v_mfma_f32_16x16x32_bf16 v[8:11], v[218:221], v[182:185], v[8:11]
	v_mfma_f32_16x16x32_bf16 v[4:7], v[208:211], v[200:203], v[4:7]
	v_mfma_f32_16x16x32_bf16 v[0:3], v[218:221], v[200:203], v[0:3]
	s_add_i32 s31, s31, 2
	s_addk_i32 s34, 0x100
	s_cmp_lt_u32 s31, 28
	s_barrier
	s_cbranch_scc1 .LBB0_526
	v_mov_b32_e32 v144, v130
	s_or_b32 s15, s15, 0x80f80
	v_and_b32_e32 v147, 15, v144
	v_bfe_u32 v146, v144, 4, 2
	v_lshlrev_b32_e32 v150, 2, v144
	v_bfe_u32 v145, v144, 6, 2
	v_lshlrev_b32_e32 v174, 4, v146
	v_lshlrev_b32_e32 v148, 6, v147
	v_and_b32_e32 v175, 32, v150
	v_lshlrev_b32_e32 v149, 12, v145
	v_bitop3_b32 v176, v174, v175, v148 bitop3:0x36
	v_add3_u32 v148, s78, v176, v149
	ds_read_b128 v[150:153], v148
	ds_read_b128 v[154:157], v148 offset:1024
	ds_read_b128 v[158:161], v148 offset:2048
	ds_read_b128 v[162:165], v148 offset:3072
	v_ashrrev_i32_e32 v148, 2, v144
	v_lshlrev_b32_e32 v178, 6, v144
	v_and_b32_e32 v148, 0xffffffc0, v148
	v_and_b32_e32 v178, 0x3c0, v178
	v_lshlrev_b32_e32 v177, 7, v148
	v_bitop3_b32 v174, v178, v175, v174 bitop3:0x36
	s_waitcnt vmcnt(0)
	v_add3_u32 v190, 0, v176, v177
	v_add3_u32 v174, 0, v174, v177
	s_mov_b32 m0, s7
	ds_read_b128 v[166:169], v190
	ds_read_b128 v[170:173], v190 offset:1024
	ds_read_b128 v[178:181], v174 offset:2048
	ds_read_b128 v[182:185], v174 offset:3072
	ds_read_b128 v[196:199], v174 offset:4096
	ds_read_b128 v[200:203], v174 offset:5120
	ds_read_b128 v[204:207], v174 offset:6144
	ds_read_b128 v[208:211], v174 offset:7168
	buffer_load_dwordx4 v134, s[48:51], s15 offen lds
	s_mov_b32 m0, s6
	s_nop 0
	buffer_load_dwordx4 v135, s[48:51], s15 offen lds
	s_barrier
	s_waitcnt lgkmcnt(0)
	s_waitcnt lgkmcnt(7)
	v_mfma_f32_16x16x32_bf16 v[126:129], v[150:153], v[166:169], v[126:129]
	v_mfma_f32_16x16x32_bf16 v[122:125], v[158:161], v[166:169], v[122:125]
	s_waitcnt lgkmcnt(5)
	v_mfma_f32_16x16x32_bf16 v[118:121], v[150:153], v[178:181], v[118:121]
	v_mfma_f32_16x16x32_bf16 v[114:117], v[158:161], v[178:181], v[114:117]
	s_waitcnt lgkmcnt(1)
	v_mfma_f32_16x16x32_bf16 v[102:105], v[150:153], v[204:207], v[102:105]
	v_mfma_f32_16x16x32_bf16 v[98:101], v[158:161], v[204:207], v[98:101]
	v_mfma_f32_16x16x32_bf16 v[126:129], v[154:157], v[170:173], v[126:129]
	v_mfma_f32_16x16x32_bf16 v[122:125], v[162:165], v[170:173], v[122:125]
	v_mfma_f32_16x16x32_bf16 v[118:121], v[154:157], v[182:185], v[118:121]
	v_mfma_f32_16x16x32_bf16 v[114:117], v[162:165], v[182:185], v[114:117]
	v_mfma_f32_16x16x32_bf16 v[110:113], v[150:153], v[196:199], v[110:113]
	v_mfma_f32_16x16x32_bf16 v[106:109], v[158:161], v[196:199], v[106:109]
	s_waitcnt lgkmcnt(0)
	v_mfma_f32_16x16x32_bf16 v[102:105], v[154:157], v[208:211], v[102:105]
	v_mfma_f32_16x16x32_bf16 v[98:101], v[162:165], v[208:211], v[98:101]
	v_mfma_f32_16x16x32_bf16 v[214:217], v[154:157], v[200:203], v[110:113]
	v_mfma_f32_16x16x32_bf16 v[218:221], v[162:165], v[200:203], v[106:109]
	v_add3_u32 v175, s77, v176, v149
	s_barrier
	ds_read_b128 v[106:109], v175
	ds_read_b128 v[110:113], v175 offset:1024
	ds_read_b128 v[222:225], v175 offset:2048
	ds_read_b128 v[226:229], v175 offset:3072
	s_barrier
	s_waitcnt lgkmcnt(0)
	s_waitcnt lgkmcnt(3)
	v_mfma_f32_16x16x32_bf16 v[94:97], v[106:109], v[166:169], v[94:97]
	s_waitcnt lgkmcnt(1)
	v_mfma_f32_16x16x32_bf16 v[82:85], v[222:225], v[178:181], v[82:85]
	v_mfma_f32_16x16x32_bf16 v[78:81], v[106:109], v[196:199], v[78:81]
	v_mfma_f32_16x16x32_bf16 v[74:77], v[222:225], v[196:199], v[74:77]
	v_mfma_f32_16x16x32_bf16 v[70:73], v[106:109], v[204:207], v[70:73]
	v_mfma_f32_16x16x32_bf16 v[66:69], v[222:225], v[204:207], v[66:69]
	v_mfma_f32_16x16x32_bf16 v[94:97], v[110:113], v[170:173], v[94:97]
	v_mfma_f32_16x16x32_bf16 v[90:93], v[222:225], v[166:169], v[90:93]
	v_mfma_f32_16x16x32_bf16 v[86:89], v[106:109], v[178:181], v[86:89]
	s_waitcnt lgkmcnt(0)
	v_mfma_f32_16x16x32_bf16 v[82:85], v[226:229], v[182:185], v[82:85]
	v_mfma_f32_16x16x32_bf16 v[78:81], v[110:113], v[200:203], v[78:81]
	v_mfma_f32_16x16x32_bf16 v[74:77], v[226:229], v[200:203], v[74:77]
	v_mfma_f32_16x16x32_bf16 v[70:73], v[110:113], v[208:211], v[70:73]
	v_mfma_f32_16x16x32_bf16 v[66:69], v[226:229], v[208:211], v[66:69]
	v_mfma_f32_16x16x32_bf16 v[166:169], v[226:229], v[170:173], v[90:93]
	v_mfma_f32_16x16x32_bf16 v[170:173], v[110:113], v[182:185], v[86:89]
	s_barrier
	s_nop 0
	ds_read_b128 v[86:89], v190 offset:16384
	ds_read_b128 v[90:93], v190 offset:17408
	ds_read_b128 v[178:181], v174 offset:18432
	ds_read_b128 v[182:185], v174 offset:19456
	ds_read_b128 v[196:199], v174 offset:20480
	ds_read_b128 v[200:203], v174 offset:21504
	ds_read_b128 v[204:207], v174 offset:22528
	ds_read_b128 v[208:211], v174 offset:23552
	s_waitcnt vmcnt(4)
	s_barrier
	s_waitcnt lgkmcnt(0)
	s_waitcnt lgkmcnt(5)
	v_mfma_f32_16x16x32_bf16 v[54:57], v[150:153], v[178:181], v[54:57]
	v_mfma_f32_16x16x32_bf16 v[50:53], v[158:161], v[178:181], v[50:53]
	v_mfma_f32_16x16x32_bf16 v[62:65], v[150:153], v[86:89], v[62:65]
	v_mfma_f32_16x16x32_bf16 v[58:61], v[158:161], v[86:89], v[58:61]
	s_waitcnt lgkmcnt(4)
	v_mfma_f32_16x16x32_bf16 v[54:57], v[154:157], v[182:185], v[54:57]
	v_mfma_f32_16x16x32_bf16 v[50:53], v[162:165], v[182:185], v[50:53]
	s_waitcnt lgkmcnt(3)
	v_mfma_f32_16x16x32_bf16 v[46:49], v[150:153], v[196:199], v[46:49]
	v_mfma_f32_16x16x32_bf16 v[42:45], v[158:161], v[196:199], v[42:45]
	s_waitcnt lgkmcnt(1)
	v_mfma_f32_16x16x32_bf16 v[38:41], v[150:153], v[204:207], v[38:41]
	v_mfma_f32_16x16x32_bf16 v[34:37], v[158:161], v[204:207], v[34:37]
	v_mfma_f32_16x16x32_bf16 v[230:233], v[154:157], v[90:93], v[62:65]
	v_mfma_f32_16x16x32_bf16 v[234:237], v[162:165], v[90:93], v[58:61]
	v_mfma_f32_16x16x32_bf16 v[238:241], v[154:157], v[200:203], v[46:49]
	v_mfma_f32_16x16x32_bf16 v[242:245], v[162:165], v[200:203], v[42:45]
	s_waitcnt lgkmcnt(0)
	v_mfma_f32_16x16x32_bf16 v[150:153], v[154:157], v[208:211], v[38:41]
	v_mfma_f32_16x16x32_bf16 v[154:157], v[162:165], v[208:211], v[34:37]
	v_mfma_f32_16x16x32_bf16 v[30:33], v[106:109], v[86:89], v[30:33]
	v_mfma_f32_16x16x32_bf16 v[26:29], v[222:225], v[86:89], v[26:29]
	v_mfma_f32_16x16x32_bf16 v[12:15], v[106:109], v[196:199], v[12:15]
	v_mfma_f32_16x16x32_bf16 v[8:11], v[222:225], v[196:199], v[8:11]
	v_mfma_f32_16x16x32_bf16 v[30:33], v[110:113], v[90:93], v[30:33]
	v_mfma_f32_16x16x32_bf16 v[26:29], v[226:229], v[90:93], v[26:29]
	v_mfma_f32_16x16x32_bf16 v[22:25], v[106:109], v[178:181], v[22:25]
	v_mfma_f32_16x16x32_bf16 v[18:21], v[222:225], v[178:181], v[18:21]
	v_mfma_f32_16x16x32_bf16 v[12:15], v[110:113], v[200:203], v[12:15]
	v_mfma_f32_16x16x32_bf16 v[8:11], v[226:229], v[200:203], v[8:11]
	v_mfma_f32_16x16x32_bf16 v[4:7], v[106:109], v[204:207], v[4:7]
	v_mfma_f32_16x16x32_bf16 v[0:3], v[222:225], v[204:207], v[0:3]
	v_mfma_f32_16x16x32_bf16 v[158:161], v[110:113], v[182:185], v[22:25]
	v_mfma_f32_16x16x32_bf16 v[162:165], v[226:229], v[182:185], v[18:21]
	v_mfma_f32_16x16x32_bf16 v[178:181], v[110:113], v[208:211], v[4:7]
	v_mfma_f32_16x16x32_bf16 v[182:185], v[226:229], v[208:211], v[0:3]
	v_add3_u32 v18, s2, v176, v149
	s_barrier
	s_nop 0
	ds_read_b128 v[0:3], v18
	ds_read_b128 v[4:7], v18 offset:1024
	ds_read_b128 v[196:199], v18 offset:2048
	ds_read_b128 v[200:203], v18 offset:3072
	ds_read_b128 v[18:21], v190 offset:32768
	ds_read_b128 v[22:25], v190 offset:33792
	ds_read_b128 v[42:45], v174 offset:34816
	ds_read_b128 v[46:49], v174 offset:35840
	ds_read_b128 v[204:207], v174 offset:36864
	ds_read_b128 v[208:211], v174 offset:37888
	ds_read_b128 v[222:225], v174 offset:38912
	ds_read_b128 v[226:229], v174 offset:39936
	s_waitcnt vmcnt(2)
	s_barrier
	s_waitcnt lgkmcnt(0)
	s_waitcnt lgkmcnt(7)
	v_mfma_f32_16x16x32_bf16 v[34:37], v[0:3], v[18:21], v[126:129]
	s_waitcnt lgkmcnt(6)
	v_mfma_f32_16x16x32_bf16 v[110:113], v[4:7], v[22:25], v[34:37]
	v_mfma_f32_16x16x32_bf16 v[34:37], v[196:199], v[18:21], v[122:125]
	v_mfma_f32_16x16x32_bf16 v[106:109], v[200:203], v[22:25], v[34:37]
	s_waitcnt lgkmcnt(5)
	v_mfma_f32_16x16x32_bf16 v[34:37], v[0:3], v[42:45], v[118:121]
	s_waitcnt lgkmcnt(4)
	v_mfma_f32_16x16x32_bf16 v[90:93], v[4:7], v[46:49], v[34:37]
	v_mfma_f32_16x16x32_bf16 v[34:37], v[196:199], v[42:45], v[114:117]
	v_mfma_f32_16x16x32_bf16 v[86:89], v[200:203], v[46:49], v[34:37]
	s_waitcnt lgkmcnt(3)
	v_mfma_f32_16x16x32_bf16 v[34:37], v[0:3], v[204:207], v[214:217]
	s_waitcnt lgkmcnt(2)
	v_mfma_f32_16x16x32_bf16 v[62:65], v[4:7], v[208:211], v[34:37]
	v_mfma_f32_16x16x32_bf16 v[34:37], v[196:199], v[204:207], v[218:221]
	v_mfma_f32_16x16x32_bf16 v[58:61], v[200:203], v[208:211], v[34:37]
	s_waitcnt lgkmcnt(1)
	v_mfma_f32_16x16x32_bf16 v[34:37], v[0:3], v[222:225], v[102:105]
	s_waitcnt lgkmcnt(0)
	v_mfma_f32_16x16x32_bf16 v[38:41], v[4:7], v[226:229], v[34:37]
	v_mfma_f32_16x16x32_bf16 v[34:37], v[196:199], v[222:225], v[98:101]
	v_mfma_f32_16x16x32_bf16 v[34:37], v[200:203], v[226:229], v[34:37]
	s_nop 0
	v_add3_u32 v98, s91, v176, v149
	s_barrier
	ds_read_b128 v[214:217], v98
	ds_read_b128 v[218:221], v98 offset:1024
	ds_read_b128 v[246:249], v98 offset:2048
	ds_read_b128 v[250:253], v98 offset:3072
	s_waitcnt vmcnt(0)
	s_barrier
	s_waitcnt lgkmcnt(0)
	s_waitcnt lgkmcnt(3)
	v_mfma_f32_16x16x32_bf16 v[94:97], v[214:217], v[18:21], v[94:97]
	s_waitcnt lgkmcnt(1)
	v_mfma_f32_16x16x32_bf16 v[18:21], v[246:249], v[18:21], v[166:169]
	s_waitcnt lgkmcnt(0)
	v_mfma_f32_16x16x32_bf16 v[122:125], v[250:253], v[22:25], v[18:21]
	v_mfma_f32_16x16x32_bf16 v[18:21], v[214:217], v[42:45], v[170:173]
	v_mfma_f32_16x16x32_bf16 v[118:121], v[218:221], v[46:49], v[18:21]
	v_mfma_f32_16x16x32_bf16 v[18:21], v[246:249], v[42:45], v[82:85]
	v_mfma_f32_16x16x32_bf16 v[114:117], v[250:253], v[46:49], v[18:21]
	v_mfma_f32_16x16x32_bf16 v[18:21], v[214:217], v[204:207], v[78:81]
	v_mfma_f32_16x16x32_bf16 v[102:105], v[218:221], v[208:211], v[18:21]
	v_mfma_f32_16x16x32_bf16 v[18:21], v[246:249], v[204:207], v[74:77]
	v_mfma_f32_16x16x32_bf16 v[126:129], v[218:221], v[22:25], v[94:97]
	v_mfma_f32_16x16x32_bf16 v[94:97], v[250:253], v[208:211], v[18:21]
	v_mfma_f32_16x16x32_bf16 v[18:21], v[214:217], v[222:225], v[70:73]
	v_mfma_f32_16x16x32_bf16 v[70:73], v[218:221], v[226:229], v[18:21]
	v_mfma_f32_16x16x32_bf16 v[18:21], v[246:249], v[222:225], v[66:69]
	v_mfma_f32_16x16x32_bf16 v[66:69], v[250:253], v[226:229], v[18:21]
	s_barrier
	ds_read_b128 v[82:85], v190 offset:49152
	ds_read_b128 v[166:169], v190 offset:50176
	ds_read_b128 v[170:173], v174 offset:51200
	ds_read_b128 v[204:207], v174 offset:52224
	ds_read_b128 v[208:211], v174 offset:53248
	ds_read_b128 v[222:225], v174 offset:54272
	ds_read_b128 v[226:229], v174 offset:55296
	ds_read_b128 v[174:177], v174 offset:56320
	s_barrier
	s_waitcnt lgkmcnt(0)
	s_waitcnt lgkmcnt(7)
	v_mfma_f32_16x16x32_bf16 v[18:21], v[0:3], v[82:85], v[230:233]
	s_waitcnt lgkmcnt(6)
	v_mfma_f32_16x16x32_bf16 v[78:81], v[4:7], v[166:169], v[18:21]
	v_mfma_f32_16x16x32_bf16 v[18:21], v[196:199], v[82:85], v[234:237]
	v_mfma_f32_16x16x32_bf16 v[74:77], v[200:203], v[166:169], v[18:21]
	s_waitcnt lgkmcnt(5)
	v_mfma_f32_16x16x32_bf16 v[18:21], v[0:3], v[170:173], v[54:57]
	s_waitcnt lgkmcnt(4)
	v_mfma_f32_16x16x32_bf16 v[46:49], v[4:7], v[204:207], v[18:21]
	v_mfma_f32_16x16x32_bf16 v[18:21], v[196:199], v[170:173], v[50:53]
	v_mfma_f32_16x16x32_bf16 v[42:45], v[200:203], v[204:207], v[18:21]
	s_waitcnt lgkmcnt(3)
	v_mfma_f32_16x16x32_bf16 v[18:21], v[0:3], v[208:211], v[238:241]
	s_waitcnt lgkmcnt(1)
	v_mfma_f32_16x16x32_bf16 v[0:3], v[0:3], v[226:229], v[150:153]
	v_mfma_f32_16x16x32_bf16 v[22:25], v[4:7], v[222:225], v[18:21]
	v_mfma_f32_16x16x32_bf16 v[18:21], v[196:199], v[208:211], v[242:245]
	s_waitcnt lgkmcnt(0)
	v_mfma_f32_16x16x32_bf16 v[4:7], v[4:7], v[174:177], v[0:3]
	v_mfma_f32_16x16x32_bf16 v[0:3], v[196:199], v[226:229], v[154:157]
	v_mfma_f32_16x16x32_bf16 v[18:21], v[200:203], v[222:225], v[18:21]
	v_mfma_f32_16x16x32_bf16 v[0:3], v[200:203], v[174:177], v[0:3]
	v_mfma_f32_16x16x32_bf16 v[26:29], v[246:249], v[82:85], v[26:29]
	v_mfma_f32_16x16x32_bf16 v[30:33], v[214:217], v[82:85], v[30:33]
	v_mfma_f32_16x16x32_bf16 v[82:85], v[250:253], v[166:169], v[26:29]
	v_mfma_f32_16x16x32_bf16 v[26:29], v[214:217], v[170:173], v[158:161]
	v_mfma_f32_16x16x32_bf16 v[54:57], v[218:221], v[204:207], v[26:29]
	v_mfma_f32_16x16x32_bf16 v[26:29], v[246:249], v[170:173], v[162:165]
	v_mfma_f32_16x16x32_bf16 v[8:11], v[246:249], v[208:211], v[8:11]
	v_mfma_f32_16x16x32_bf16 v[50:53], v[250:253], v[204:207], v[26:29]
	v_mfma_f32_16x16x32_bf16 v[12:15], v[214:217], v[208:211], v[12:15]
	v_mfma_f32_16x16x32_bf16 v[26:29], v[250:253], v[222:225], v[8:11]
	v_mfma_f32_16x16x32_bf16 v[8:11], v[214:217], v[226:229], v[178:181]
	v_mfma_f32_16x16x32_bf16 v[98:101], v[218:221], v[166:169], v[30:33]
	v_mfma_f32_16x16x32_bf16 v[30:33], v[218:221], v[222:225], v[12:15]
	v_mfma_f32_16x16x32_bf16 v[12:15], v[218:221], v[174:177], v[8:11]
	v_mfma_f32_16x16x32_bf16 v[8:11], v[246:249], v[226:229], v[182:185]
	v_mfma_f32_16x16x32_bf16 v[8:11], v[250:253], v[174:177], v[8:11]
	s_setprio 0
	s_movk_i32 s1, 0x100
	v_cmp_gt_u32_e32 vcc, s1, v144
	s_barrier
	s_and_saveexec_b64 s[6:7], vcc
	s_cbranch_execz .LBB0_529
	s_barrier

.LBB0_646:
	ds_read_b128 v[144:147], v136
	ds_read_b128 v[148:151], v136 offset:1024
	ds_read_b128 v[152:155], v136 offset:2048
	ds_read_b128 v[156:159], v136 offset:3072
	s_add_i32 s39, s19, s38
	s_add_i32 s61, s39, 0x80080
	s_mov_b32 m0, s13
	ds_read_b128 v[160:163], v137
	ds_read_b128 v[164:167], v137 offset:1024
	ds_read_b128 v[168:171], v138
	ds_read_b128 v[172:175], v138 offset:1024
	ds_read_b128 v[176:179], v139
	ds_read_b128 v[180:183], v139 offset:1024
	ds_read_b128 v[196:199], v140
	ds_read_b128 v[200:203], v140 offset:1024
	buffer_load_dwordx4 v134, s[48:51], s61 offen lds
	s_mov_b32 m0, s12
	s_nop 0
	buffer_load_dwordx4 v135, s[48:51], s61 offen lds
	s_waitcnt lgkmcnt(8)
	s_barrier
	s_waitcnt lgkmcnt(0)
	s_waitcnt lgkmcnt(0)
	v_mfma_f32_16x16x32_bf16 v[126:129], v[144:147], v[160:163], v[126:129]
	v_mfma_f32_16x16x32_bf16 v[122:125], v[152:155], v[160:163], v[122:125]
	v_mfma_f32_16x16x32_bf16 v[118:121], v[144:147], v[168:171], v[118:121]
	v_mfma_f32_16x16x32_bf16 v[114:117], v[152:155], v[168:171], v[114:117]
	v_mfma_f32_16x16x32_bf16 v[110:113], v[144:147], v[176:179], v[110:113]
	v_mfma_f32_16x16x32_bf16 v[106:109], v[152:155], v[176:179], v[106:109]
	v_mfma_f32_16x16x32_bf16 v[102:105], v[144:147], v[196:199], v[102:105]
	v_mfma_f32_16x16x32_bf16 v[98:101], v[152:155], v[196:199], v[98:101]
	v_mfma_f32_16x16x32_bf16 v[126:129], v[148:151], v[164:167], v[126:129]
	v_mfma_f32_16x16x32_bf16 v[122:125], v[156:159], v[164:167], v[122:125]
	v_mfma_f32_16x16x32_bf16 v[118:121], v[148:151], v[172:175], v[118:121]
	v_mfma_f32_16x16x32_bf16 v[114:117], v[156:159], v[172:175], v[114:117]
	v_mfma_f32_16x16x32_bf16 v[110:113], v[148:151], v[180:183], v[110:113]
	v_mfma_f32_16x16x32_bf16 v[106:109], v[156:159], v[180:183], v[106:109]
	v_mfma_f32_16x16x32_bf16 v[102:105], v[148:151], v[200:203], v[102:105]
	v_mfma_f32_16x16x32_bf16 v[98:101], v[156:159], v[200:203], v[98:101]
	s_barrier
	s_add_i32 s61, s20, s38
	s_add_i32 s62, s61, 0x100
	s_mov_b32 m0, s22
	ds_read_b128 v[204:207], v141
	ds_read_b128 v[208:211], v141 offset:1024
	ds_read_b128 v[214:217], v141 offset:2048
	ds_read_b128 v[218:221], v141 offset:3072
	buffer_load_dwordx4 v134, s[52:55], s62 offen lds
	s_mov_b32 m0, s23
	s_nop 0
	buffer_load_dwordx4 v135, s[52:55], s62 offen lds
	s_barrier
	s_waitcnt lgkmcnt(0)
	s_waitcnt lgkmcnt(0)
	v_mfma_f32_16x16x32_bf16 v[94:97], v[204:207], v[160:163], v[94:97]
	v_mfma_f32_16x16x32_bf16 v[90:93], v[214:217], v[160:163], v[90:93]
	v_mfma_f32_16x16x32_bf16 v[86:89], v[204:207], v[168:171], v[86:89]
	v_mfma_f32_16x16x32_bf16 v[82:85], v[214:217], v[168:171], v[82:85]
	v_mfma_f32_16x16x32_bf16 v[78:81], v[204:207], v[176:179], v[78:81]
	v_mfma_f32_16x16x32_bf16 v[74:77], v[214:217], v[176:179], v[74:77]
	v_mfma_f32_16x16x32_bf16 v[70:73], v[204:207], v[196:199], v[70:73]
	v_mfma_f32_16x16x32_bf16 v[66:69], v[214:217], v[196:199], v[66:69]
	v_mfma_f32_16x16x32_bf16 v[94:97], v[208:211], v[164:167], v[94:97]
	v_mfma_f32_16x16x32_bf16 v[90:93], v[218:221], v[164:167], v[90:93]
	v_mfma_f32_16x16x32_bf16 v[86:89], v[208:211], v[172:175], v[86:89]
	v_mfma_f32_16x16x32_bf16 v[82:85], v[218:221], v[172:175], v[82:85]
	v_mfma_f32_16x16x32_bf16 v[78:81], v[208:211], v[180:183], v[78:81]
	v_mfma_f32_16x16x32_bf16 v[74:77], v[218:221], v[180:183], v[74:77]
	v_mfma_f32_16x16x32_bf16 v[70:73], v[208:211], v[200:203], v[70:73]
	v_mfma_f32_16x16x32_bf16 v[66:69], v[218:221], v[200:203], v[66:69]
	s_add_i32 s62, s39, 0x100
	s_mov_b32 m0, s21
	s_barrier
	ds_read_b128 v[160:163], v137 offset:16384
	ds_read_b128 v[164:167], v137 offset:17408
	ds_read_b128 v[168:171], v138 offset:16384
	ds_read_b128 v[172:175], v138 offset:17408
	ds_read_b128 v[176:179], v139 offset:16384
	ds_read_b128 v[180:183], v139 offset:17408
	ds_read_b128 v[196:199], v140 offset:16384
	ds_read_b128 v[200:203], v140 offset:17408
	buffer_load_dwordx4 v134, s[48:51], s62 offen lds
	s_mov_b32 m0, s24
	s_nop 0
	buffer_load_dwordx4 v135, s[48:51], s62 offen lds
	s_barrier
	s_waitcnt lgkmcnt(0)
	s_waitcnt lgkmcnt(0)
	v_mfma_f32_16x16x32_bf16 v[62:65], v[144:147], v[160:163], v[62:65]
	v_mfma_f32_16x16x32_bf16 v[58:61], v[152:155], v[160:163], v[58:61]
	v_mfma_f32_16x16x32_bf16 v[54:57], v[144:147], v[168:171], v[54:57]
	v_mfma_f32_16x16x32_bf16 v[50:53], v[152:155], v[168:171], v[50:53]
	v_mfma_f32_16x16x32_bf16 v[46:49], v[144:147], v[176:179], v[46:49]
	v_mfma_f32_16x16x32_bf16 v[42:45], v[152:155], v[176:179], v[42:45]
	v_mfma_f32_16x16x32_bf16 v[38:41], v[144:147], v[196:199], v[38:41]
	v_mfma_f32_16x16x32_bf16 v[34:37], v[152:155], v[196:199], v[34:37]
	v_mfma_f32_16x16x32_bf16 v[62:65], v[148:151], v[164:167], v[62:65]
	v_mfma_f32_16x16x32_bf16 v[58:61], v[156:159], v[164:167], v[58:61]
	v_mfma_f32_16x16x32_bf16 v[54:57], v[148:151], v[172:175], v[54:57]
	v_mfma_f32_16x16x32_bf16 v[50:53], v[156:159], v[172:175], v[50:53]
	v_mfma_f32_16x16x32_bf16 v[46:49], v[148:151], v[180:183], v[46:49]
	v_mfma_f32_16x16x32_bf16 v[42:45], v[156:159], v[180:183], v[42:45]
	v_mfma_f32_16x16x32_bf16 v[38:41], v[148:151], v[200:203], v[38:41]
	v_mfma_f32_16x16x32_bf16 v[34:37], v[156:159], v[200:203], v[34:37]
	s_barrier
	s_add_i32 s62, s61, 0x80100
	s_mov_b32 m0, s25
	s_nop 0
	buffer_load_dwordx4 v134, s[52:55], s62 offen lds
	s_mov_b32 m0, s26
	s_nop 0
	buffer_load_dwordx4 v135, s[52:55], s62 offen lds
	s_waitcnt vmcnt(6)
	s_barrier
	v_mfma_f32_16x16x32_bf16 v[30:33], v[204:207], v[160:163], v[30:33]
	v_mfma_f32_16x16x32_bf16 v[26:29], v[214:217], v[160:163], v[26:29]
	v_mfma_f32_16x16x32_bf16 v[22:25], v[204:207], v[168:171], v[22:25]
	v_mfma_f32_16x16x32_bf16 v[18:21], v[214:217], v[168:171], v[18:21]
	v_mfma_f32_16x16x32_bf16 v[12:15], v[204:207], v[176:179], v[12:15]
	v_mfma_f32_16x16x32_bf16 v[8:11], v[214:217], v[176:179], v[8:11]
	v_mfma_f32_16x16x32_bf16 v[4:7], v[204:207], v[196:199], v[4:7]
	v_mfma_f32_16x16x32_bf16 v[0:3], v[214:217], v[196:199], v[0:3]
	v_mfma_f32_16x16x32_bf16 v[30:33], v[208:211], v[164:167], v[30:33]
	v_mfma_f32_16x16x32_bf16 v[26:29], v[218:221], v[164:167], v[26:29]
	v_mfma_f32_16x16x32_bf16 v[22:25], v[208:211], v[172:175], v[22:25]
	v_mfma_f32_16x16x32_bf16 v[18:21], v[218:221], v[172:175], v[18:21]
	v_mfma_f32_16x16x32_bf16 v[12:15], v[208:211], v[180:183], v[12:15]
	v_mfma_f32_16x16x32_bf16 v[8:11], v[218:221], v[180:183], v[8:11]
	v_mfma_f32_16x16x32_bf16 v[4:7], v[208:211], v[200:203], v[4:7]
	v_mfma_f32_16x16x32_bf16 v[0:3], v[218:221], v[200:203], v[0:3]
	s_barrier
	ds_read_b128 v[144:147], v142
	ds_read_b128 v[148:151], v142 offset:1024
	ds_read_b128 v[152:155], v142 offset:2048
	ds_read_b128 v[156:159], v142 offset:3072
	s_add_i32 s62, s39, 0x80100
	s_mov_b32 m0, s27
	ds_read_b128 v[160:163], v137 offset:32768
	ds_read_b128 v[164:167], v137 offset:33792
	ds_read_b128 v[168:171], v138 offset:32768
	ds_read_b128 v[172:175], v138 offset:33792
	ds_read_b128 v[176:179], v139 offset:32768
	ds_read_b128 v[180:183], v139 offset:33792
	ds_read_b128 v[196:199], v140 offset:32768
	ds_read_b128 v[200:203], v140 offset:33792
	buffer_load_dwordx4 v134, s[48:51], s62 offen lds
	s_mov_b32 m0, s28
	s_nop 0
	buffer_load_dwordx4 v135, s[48:51], s62 offen lds
	s_waitcnt lgkmcnt(8)
	s_barrier
	s_waitcnt lgkmcnt(0)
	s_waitcnt lgkmcnt(0)
	v_mfma_f32_16x16x32_bf16 v[126:129], v[144:147], v[160:163], v[126:129]
	v_mfma_f32_16x16x32_bf16 v[122:125], v[152:155], v[160:163], v[122:125]
	v_mfma_f32_16x16x32_bf16 v[118:121], v[144:147], v[168:171], v[118:121]
	v_mfma_f32_16x16x32_bf16 v[114:117], v[152:155], v[168:171], v[114:117]
	v_mfma_f32_16x16x32_bf16 v[110:113], v[144:147], v[176:179], v[110:113]
	v_mfma_f32_16x16x32_bf16 v[106:109], v[152:155], v[176:179], v[106:109]
	v_mfma_f32_16x16x32_bf16 v[102:105], v[144:147], v[196:199], v[102:105]
	v_mfma_f32_16x16x32_bf16 v[98:101], v[152:155], v[196:199], v[98:101]
	v_mfma_f32_16x16x32_bf16 v[126:129], v[148:151], v[164:167], v[126:129]
	v_mfma_f32_16x16x32_bf16 v[122:125], v[156:159], v[164:167], v[122:125]
	v_mfma_f32_16x16x32_bf16 v[118:121], v[148:151], v[172:175], v[118:121]
	v_mfma_f32_16x16x32_bf16 v[114:117], v[156:159], v[172:175], v[114:117]
	v_mfma_f32_16x16x32_bf16 v[110:113], v[148:151], v[180:183], v[110:113]
	v_mfma_f32_16x16x32_bf16 v[106:109], v[156:159], v[180:183], v[106:109]
	v_mfma_f32_16x16x32_bf16 v[102:105], v[148:151], v[200:203], v[102:105]
	v_mfma_f32_16x16x32_bf16 v[98:101], v[156:159], v[200:203], v[98:101]
	s_barrier
	s_add_i32 s62, s61, 0x180
	s_mov_b32 m0, s29
	ds_read_b128 v[204:207], v143
	ds_read_b128 v[208:211], v143 offset:1024
	ds_read_b128 v[214:217], v143 offset:2048
	ds_read_b128 v[218:221], v143 offset:3072
	buffer_load_dwordx4 v134, s[52:55], s62 offen lds
	s_mov_b32 m0, s30
	s_nop 0
	buffer_load_dwordx4 v135, s[52:55], s62 offen lds
	s_barrier
	s_waitcnt lgkmcnt(0)
	s_waitcnt lgkmcnt(0)
	v_mfma_f32_16x16x32_bf16 v[94:97], v[204:207], v[160:163], v[94:97]
	v_mfma_f32_16x16x32_bf16 v[90:93], v[214:217], v[160:163], v[90:93]
	v_mfma_f32_16x16x32_bf16 v[86:89], v[204:207], v[168:171], v[86:89]
	v_mfma_f32_16x16x32_bf16 v[82:85], v[214:217], v[168:171], v[82:85]
	v_mfma_f32_16x16x32_bf16 v[78:81], v[204:207], v[176:179], v[78:81]
	v_mfma_f32_16x16x32_bf16 v[74:77], v[214:217], v[176:179], v[74:77]
	v_mfma_f32_16x16x32_bf16 v[70:73], v[204:207], v[196:199], v[70:73]
	v_mfma_f32_16x16x32_bf16 v[66:69], v[214:217], v[196:199], v[66:69]
	v_mfma_f32_16x16x32_bf16 v[94:97], v[208:211], v[164:167], v[94:97]
	v_mfma_f32_16x16x32_bf16 v[90:93], v[218:221], v[164:167], v[90:93]
	v_mfma_f32_16x16x32_bf16 v[86:89], v[208:211], v[172:175], v[86:89]
	v_mfma_f32_16x16x32_bf16 v[82:85], v[218:221], v[172:175], v[82:85]
	v_mfma_f32_16x16x32_bf16 v[78:81], v[208:211], v[180:183], v[78:81]
	v_mfma_f32_16x16x32_bf16 v[74:77], v[218:221], v[180:183], v[74:77]
	v_mfma_f32_16x16x32_bf16 v[70:73], v[208:211], v[200:203], v[70:73]
	v_mfma_f32_16x16x32_bf16 v[66:69], v[218:221], v[200:203], v[66:69]
	s_addk_i32 s39, 0x180
	s_mov_b32 m0, s31
	s_barrier
	ds_read_b128 v[160:163], v137 offset:49152
	ds_read_b128 v[164:167], v137 offset:50176
	ds_read_b128 v[168:171], v138 offset:49152
	ds_read_b128 v[172:175], v138 offset:50176
	ds_read_b128 v[176:179], v139 offset:49152
	ds_read_b128 v[180:183], v139 offset:50176
	ds_read_b128 v[196:199], v140 offset:49152
	ds_read_b128 v[200:203], v140 offset:50176
	buffer_load_dwordx4 v134, s[48:51], s39 offen lds
	s_mov_b32 m0, s34
	s_nop 0
	buffer_load_dwordx4 v135, s[48:51], s39 offen lds
	s_barrier
	s_waitcnt lgkmcnt(0)
	s_waitcnt lgkmcnt(0)
	v_mfma_f32_16x16x32_bf16 v[62:65], v[144:147], v[160:163], v[62:65]
	v_mfma_f32_16x16x32_bf16 v[58:61], v[152:155], v[160:163], v[58:61]
	v_mfma_f32_16x16x32_bf16 v[54:57], v[144:147], v[168:171], v[54:57]
	v_mfma_f32_16x16x32_bf16 v[50:53], v[152:155], v[168:171], v[50:53]
	v_mfma_f32_16x16x32_bf16 v[46:49], v[144:147], v[176:179], v[46:49]
	v_mfma_f32_16x16x32_bf16 v[42:45], v[152:155], v[176:179], v[42:45]
	v_mfma_f32_16x16x32_bf16 v[38:41], v[144:147], v[196:199], v[38:41]
	v_mfma_f32_16x16x32_bf16 v[34:37], v[152:155], v[196:199], v[34:37]
	v_mfma_f32_16x16x32_bf16 v[62:65], v[148:151], v[164:167], v[62:65]
	v_mfma_f32_16x16x32_bf16 v[58:61], v[156:159], v[164:167], v[58:61]
	v_mfma_f32_16x16x32_bf16 v[54:57], v[148:151], v[172:175], v[54:57]
	v_mfma_f32_16x16x32_bf16 v[50:53], v[156:159], v[172:175], v[50:53]
	v_mfma_f32_16x16x32_bf16 v[46:49], v[148:151], v[180:183], v[46:49]
	v_mfma_f32_16x16x32_bf16 v[42:45], v[156:159], v[180:183], v[42:45]
	v_mfma_f32_16x16x32_bf16 v[38:41], v[148:151], v[200:203], v[38:41]
	v_mfma_f32_16x16x32_bf16 v[34:37], v[156:159], v[200:203], v[34:37]
	s_barrier
	s_add_i32 s61, s61, 0x80180
	s_mov_b32 m0, s35
	s_nop 0
	buffer_load_dwordx4 v134, s[52:55], s61 offen lds
	s_mov_b32 m0, s36
	s_nop 0
	buffer_load_dwordx4 v135, s[52:55], s61 offen lds
	s_waitcnt vmcnt(6)
	s_barrier
	v_mfma_f32_16x16x32_bf16 v[30:33], v[204:207], v[160:163], v[30:33]
	v_mfma_f32_16x16x32_bf16 v[26:29], v[214:217], v[160:163], v[26:29]
	v_mfma_f32_16x16x32_bf16 v[22:25], v[204:207], v[168:171], v[22:25]
	v_mfma_f32_16x16x32_bf16 v[18:21], v[214:217], v[168:171], v[18:21]
	v_mfma_f32_16x16x32_bf16 v[12:15], v[204:207], v[176:179], v[12:15]
	v_mfma_f32_16x16x32_bf16 v[8:11], v[214:217], v[176:179], v[8:11]
	v_mfma_f32_16x16x32_bf16 v[4:7], v[204:207], v[196:199], v[4:7]
	v_mfma_f32_16x16x32_bf16 v[0:3], v[214:217], v[196:199], v[0:3]
	v_mfma_f32_16x16x32_bf16 v[30:33], v[208:211], v[164:167], v[30:33]
	v_mfma_f32_16x16x32_bf16 v[26:29], v[218:221], v[164:167], v[26:29]
	v_mfma_f32_16x16x32_bf16 v[22:25], v[208:211], v[172:175], v[22:25]
	v_mfma_f32_16x16x32_bf16 v[18:21], v[218:221], v[172:175], v[18:21]
	v_mfma_f32_16x16x32_bf16 v[12:15], v[208:211], v[180:183], v[12:15]
	v_mfma_f32_16x16x32_bf16 v[8:11], v[218:221], v[180:183], v[8:11]
	v_mfma_f32_16x16x32_bf16 v[4:7], v[208:211], v[200:203], v[4:7]
	v_mfma_f32_16x16x32_bf16 v[0:3], v[218:221], v[200:203], v[0:3]
	s_add_i32 s37, s37, 2
	s_addk_i32 s38, 0x100
	s_cmp_lt_u32 s37, 28
	s_barrier
	s_cbranch_scc1 .LBB0_646
	v_mov_b32_e32 v144, v130
	s_or_b32 s19, s19, 0x80f80
	v_and_b32_e32 v147, 15, v144
	v_bfe_u32 v146, v144, 4, 2
	v_lshlrev_b32_e32 v150, 2, v144
	v_bfe_u32 v145, v144, 6, 2
	v_lshlrev_b32_e32 v174, 4, v146
	v_lshlrev_b32_e32 v148, 6, v147
	v_and_b32_e32 v175, 32, v150
	v_lshlrev_b32_e32 v149, 12, v145
	v_bitop3_b32 v190, v174, v175, v148 bitop3:0x36
	v_add3_u32 v148, s78, v190, v149
	ds_read_b128 v[150:153], v148
	ds_read_b128 v[154:157], v148 offset:1024
	ds_read_b128 v[158:161], v148 offset:2048
	ds_read_b128 v[162:165], v148 offset:3072
	v_ashrrev_i32_e32 v148, 2, v144
	v_lshlrev_b32_e32 v177, 6, v144
	v_and_b32_e32 v148, 0xffffffc0, v148
	v_and_b32_e32 v177, 0x3c0, v177
	v_lshlrev_b32_e32 v176, 7, v148
	v_bitop3_b32 v174, v177, v175, v174 bitop3:0x36
	s_waitcnt vmcnt(0)
	v_add3_u32 v250, 0, v190, v176
	v_add3_u32 v251, 0, v174, v176
	s_mov_b32 m0, s13
	ds_read_b128 v[166:169], v250
	ds_read_b128 v[170:173], v250 offset:1024
	ds_read_b128 v[174:177], v251 offset:2048
	ds_read_b128 v[178:181], v251 offset:3072
	ds_read_b128 v[182:185], v251 offset:4096
	ds_read_b128 v[196:199], v251 offset:5120
	ds_read_b128 v[200:203], v251 offset:6144
	ds_read_b128 v[204:207], v251 offset:7168
	buffer_load_dwordx4 v134, s[48:51], s19 offen lds
	s_mov_b32 m0, s12
	s_nop 0
	buffer_load_dwordx4 v135, s[48:51], s19 offen lds
	s_barrier
	s_waitcnt lgkmcnt(0)
	s_waitcnt lgkmcnt(0)
	v_mfma_f32_16x16x32_bf16 v[126:129], v[150:153], v[166:169], v[126:129]
	v_mfma_f32_16x16x32_bf16 v[122:125], v[158:161], v[166:169], v[122:125]
	v_mfma_f32_16x16x32_bf16 v[118:121], v[150:153], v[174:177], v[118:121]
	v_mfma_f32_16x16x32_bf16 v[114:117], v[158:161], v[174:177], v[114:117]
	v_mfma_f32_16x16x32_bf16 v[102:105], v[150:153], v[200:203], v[102:105]
	v_mfma_f32_16x16x32_bf16 v[98:101], v[158:161], v[200:203], v[98:101]
	v_mfma_f32_16x16x32_bf16 v[126:129], v[154:157], v[170:173], v[126:129]
	v_mfma_f32_16x16x32_bf16 v[122:125], v[162:165], v[170:173], v[122:125]
	v_mfma_f32_16x16x32_bf16 v[118:121], v[154:157], v[178:181], v[118:121]
	v_mfma_f32_16x16x32_bf16 v[114:117], v[162:165], v[178:181], v[114:117]
	v_mfma_f32_16x16x32_bf16 v[110:113], v[150:153], v[182:185], v[110:113]
	v_mfma_f32_16x16x32_bf16 v[106:109], v[158:161], v[182:185], v[106:109]
	v_mfma_f32_16x16x32_bf16 v[102:105], v[154:157], v[204:207], v[102:105]
	v_mfma_f32_16x16x32_bf16 v[98:101], v[162:165], v[204:207], v[98:101]
	v_mfma_f32_16x16x32_bf16 v[208:211], v[154:157], v[196:199], v[110:113]
	v_mfma_f32_16x16x32_bf16 v[214:217], v[162:165], v[196:199], v[106:109]
	v_add3_u32 v222, s77, v190, v149
	s_barrier
	s_nop 0
	ds_read_b128 v[106:109], v222
	ds_read_b128 v[110:113], v222 offset:1024
	ds_read_b128 v[218:221], v222 offset:2048
	ds_read_b128 v[222:225], v222 offset:3072
	s_barrier
	s_waitcnt lgkmcnt(0)
	s_waitcnt lgkmcnt(0)
	v_mfma_f32_16x16x32_bf16 v[94:97], v[106:109], v[166:169], v[94:97]
	v_mfma_f32_16x16x32_bf16 v[82:85], v[218:221], v[174:177], v[82:85]
	v_mfma_f32_16x16x32_bf16 v[78:81], v[106:109], v[182:185], v[78:81]
	v_mfma_f32_16x16x32_bf16 v[74:77], v[218:221], v[182:185], v[74:77]
	v_mfma_f32_16x16x32_bf16 v[70:73], v[106:109], v[200:203], v[70:73]
	v_mfma_f32_16x16x32_bf16 v[66:69], v[218:221], v[200:203], v[66:69]
	v_mfma_f32_16x16x32_bf16 v[94:97], v[110:113], v[170:173], v[94:97]
	v_mfma_f32_16x16x32_bf16 v[90:93], v[218:221], v[166:169], v[90:93]
	v_mfma_f32_16x16x32_bf16 v[86:89], v[106:109], v[174:177], v[86:89]
	v_mfma_f32_16x16x32_bf16 v[82:85], v[222:225], v[178:181], v[82:85]
	v_mfma_f32_16x16x32_bf16 v[78:81], v[110:113], v[196:199], v[78:81]
	v_mfma_f32_16x16x32_bf16 v[74:77], v[222:225], v[196:199], v[74:77]
	v_mfma_f32_16x16x32_bf16 v[70:73], v[110:113], v[204:207], v[70:73]
	v_mfma_f32_16x16x32_bf16 v[66:69], v[222:225], v[204:207], v[66:69]
	v_mfma_f32_16x16x32_bf16 v[166:169], v[222:225], v[170:173], v[90:93]
	v_mfma_f32_16x16x32_bf16 v[170:173], v[110:113], v[178:181], v[86:89]
	s_barrier
	s_nop 0
	ds_read_b128 v[86:89], v250 offset:16384
	ds_read_b128 v[90:93], v250 offset:17408
	ds_read_b128 v[174:177], v251 offset:18432
	ds_read_b128 v[178:181], v251 offset:19456
	ds_read_b128 v[182:185], v251 offset:20480
	ds_read_b128 v[196:199], v251 offset:21504
	ds_read_b128 v[200:203], v251 offset:22528
	ds_read_b128 v[204:207], v251 offset:23552
	s_waitcnt vmcnt(4)
	s_barrier
	s_waitcnt lgkmcnt(0)
	s_waitcnt lgkmcnt(0)
	v_mfma_f32_16x16x32_bf16 v[54:57], v[150:153], v[174:177], v[54:57]
	v_mfma_f32_16x16x32_bf16 v[50:53], v[158:161], v[174:177], v[50:53]
	v_mfma_f32_16x16x32_bf16 v[62:65], v[150:153], v[86:89], v[62:65]
	v_mfma_f32_16x16x32_bf16 v[58:61], v[158:161], v[86:89], v[58:61]
	v_mfma_f32_16x16x32_bf16 v[54:57], v[154:157], v[178:181], v[54:57]
	v_mfma_f32_16x16x32_bf16 v[50:53], v[162:165], v[178:181], v[50:53]
	v_mfma_f32_16x16x32_bf16 v[46:49], v[150:153], v[182:185], v[46:49]
	v_mfma_f32_16x16x32_bf16 v[42:45], v[158:161], v[182:185], v[42:45]
	v_mfma_f32_16x16x32_bf16 v[38:41], v[150:153], v[200:203], v[38:41]
	v_mfma_f32_16x16x32_bf16 v[34:37], v[158:161], v[200:203], v[34:37]
	v_mfma_f32_16x16x32_bf16 v[226:229], v[154:157], v[90:93], v[62:65]
	v_mfma_f32_16x16x32_bf16 v[230:233], v[162:165], v[90:93], v[58:61]
	v_mfma_f32_16x16x32_bf16 v[234:237], v[154:157], v[196:199], v[46:49]
	v_mfma_f32_16x16x32_bf16 v[238:241], v[162:165], v[196:199], v[42:45]
	v_mfma_f32_16x16x32_bf16 v[150:153], v[154:157], v[204:207], v[38:41]
	v_mfma_f32_16x16x32_bf16 v[154:157], v[162:165], v[204:207], v[34:37]
	v_mfma_f32_16x16x32_bf16 v[30:33], v[106:109], v[86:89], v[30:33]
	v_mfma_f32_16x16x32_bf16 v[26:29], v[218:221], v[86:89], v[26:29]
	v_mfma_f32_16x16x32_bf16 v[12:15], v[106:109], v[182:185], v[12:15]
	v_mfma_f32_16x16x32_bf16 v[8:11], v[218:221], v[182:185], v[8:11]
	v_mfma_f32_16x16x32_bf16 v[30:33], v[110:113], v[90:93], v[30:33]
	v_mfma_f32_16x16x32_bf16 v[26:29], v[222:225], v[90:93], v[26:29]
	v_mfma_f32_16x16x32_bf16 v[22:25], v[106:109], v[174:177], v[22:25]
	v_mfma_f32_16x16x32_bf16 v[18:21], v[218:221], v[174:177], v[18:21]
	v_mfma_f32_16x16x32_bf16 v[12:15], v[110:113], v[196:199], v[12:15]
	v_mfma_f32_16x16x32_bf16 v[8:11], v[222:225], v[196:199], v[8:11]
	v_mfma_f32_16x16x32_bf16 v[4:7], v[106:109], v[200:203], v[4:7]
	v_mfma_f32_16x16x32_bf16 v[0:3], v[218:221], v[200:203], v[0:3]
	v_mfma_f32_16x16x32_bf16 v[158:161], v[110:113], v[178:181], v[22:25]
	v_mfma_f32_16x16x32_bf16 v[162:165], v[222:225], v[178:181], v[18:21]
	v_mfma_f32_16x16x32_bf16 v[174:177], v[110:113], v[204:207], v[4:7]
	v_mfma_f32_16x16x32_bf16 v[178:181], v[222:225], v[204:207], v[0:3]
	v_add3_u32 v18, s2, v190, v149
	s_barrier
	s_nop 0
	ds_read_b128 v[0:3], v18
	ds_read_b128 v[4:7], v18 offset:1024
	ds_read_b128 v[182:185], v18 offset:2048
	ds_read_b128 v[196:199], v18 offset:3072
	ds_read_b128 v[18:21], v250 offset:32768
	ds_read_b128 v[22:25], v250 offset:33792
	ds_read_b128 v[42:45], v251 offset:34816
	ds_read_b128 v[46:49], v251 offset:35840
	ds_read_b128 v[200:203], v251 offset:36864
	ds_read_b128 v[204:207], v251 offset:37888
	ds_read_b128 v[218:221], v251 offset:38912
	ds_read_b128 v[222:225], v251 offset:39936
	s_waitcnt vmcnt(2)
	s_barrier
	s_waitcnt lgkmcnt(0)
	s_waitcnt lgkmcnt(0)
	v_mfma_f32_16x16x32_bf16 v[34:37], v[0:3], v[18:21], v[126:129]
	v_mfma_f32_16x16x32_bf16 v[110:113], v[4:7], v[22:25], v[34:37]
	v_mfma_f32_16x16x32_bf16 v[34:37], v[182:185], v[18:21], v[122:125]
	v_mfma_f32_16x16x32_bf16 v[106:109], v[196:199], v[22:25], v[34:37]
	v_mfma_f32_16x16x32_bf16 v[34:37], v[0:3], v[42:45], v[118:121]
	v_mfma_f32_16x16x32_bf16 v[90:93], v[4:7], v[46:49], v[34:37]
	v_mfma_f32_16x16x32_bf16 v[34:37], v[182:185], v[42:45], v[114:117]
	v_mfma_f32_16x16x32_bf16 v[86:89], v[196:199], v[46:49], v[34:37]
	v_mfma_f32_16x16x32_bf16 v[34:37], v[0:3], v[200:203], v[208:211]
	v_mfma_f32_16x16x32_bf16 v[62:65], v[4:7], v[204:207], v[34:37]
	v_mfma_f32_16x16x32_bf16 v[34:37], v[182:185], v[200:203], v[214:217]
	v_mfma_f32_16x16x32_bf16 v[58:61], v[196:199], v[204:207], v[34:37]
	v_mfma_f32_16x16x32_bf16 v[34:37], v[0:3], v[218:221], v[102:105]
	v_mfma_f32_16x16x32_bf16 v[38:41], v[4:7], v[222:225], v[34:37]
	v_mfma_f32_16x16x32_bf16 v[34:37], v[182:185], v[218:221], v[98:101]
	v_mfma_f32_16x16x32_bf16 v[34:37], v[196:199], v[222:225], v[34:37]
	s_nop 0
	v_add3_u32 v98, s91, v190, v149
	s_barrier
	ds_read_b128 v[208:211], v98
	ds_read_b128 v[214:217], v98 offset:1024
	ds_read_b128 v[242:245], v98 offset:2048
	ds_read_b128 v[246:249], v98 offset:3072
	s_waitcnt vmcnt(0)
	s_barrier
	s_waitcnt lgkmcnt(0)
	s_waitcnt lgkmcnt(0)
	v_mfma_f32_16x16x32_bf16 v[94:97], v[208:211], v[18:21], v[94:97]
	v_mfma_f32_16x16x32_bf16 v[18:21], v[242:245], v[18:21], v[166:169]
	v_mfma_f32_16x16x32_bf16 v[122:125], v[246:249], v[22:25], v[18:21]
	v_mfma_f32_16x16x32_bf16 v[18:21], v[208:211], v[42:45], v[170:173]
	v_mfma_f32_16x16x32_bf16 v[118:121], v[214:217], v[46:49], v[18:21]
	v_mfma_f32_16x16x32_bf16 v[18:21], v[242:245], v[42:45], v[82:85]
	v_mfma_f32_16x16x32_bf16 v[114:117], v[246:249], v[46:49], v[18:21]
	v_mfma_f32_16x16x32_bf16 v[18:21], v[208:211], v[200:203], v[78:81]
	v_mfma_f32_16x16x32_bf16 v[102:105], v[214:217], v[204:207], v[18:21]
	v_mfma_f32_16x16x32_bf16 v[18:21], v[242:245], v[200:203], v[74:77]
	v_mfma_f32_16x16x32_bf16 v[126:129], v[214:217], v[22:25], v[94:97]
	v_mfma_f32_16x16x32_bf16 v[94:97], v[246:249], v[204:207], v[18:21]
	v_mfma_f32_16x16x32_bf16 v[18:21], v[208:211], v[218:221], v[70:73]
	v_mfma_f32_16x16x32_bf16 v[70:73], v[214:217], v[222:225], v[18:21]
	v_mfma_f32_16x16x32_bf16 v[18:21], v[242:245], v[218:221], v[66:69]
	v_mfma_f32_16x16x32_bf16 v[66:69], v[246:249], v[222:225], v[18:21]
	s_barrier
	ds_read_b128 v[82:85], v250 offset:49152
	ds_read_b128 v[166:169], v250 offset:50176
	ds_read_b128 v[170:173], v251 offset:51200
	ds_read_b128 v[200:203], v251 offset:52224
	ds_read_b128 v[204:207], v251 offset:53248
	ds_read_b128 v[218:221], v251 offset:54272
	ds_read_b128 v[222:225], v251 offset:55296
	ds_read_b128 v[250:253], v251 offset:56320
	s_barrier
	s_waitcnt lgkmcnt(0)
	s_waitcnt lgkmcnt(0)
	v_mfma_f32_16x16x32_bf16 v[18:21], v[0:3], v[82:85], v[226:229]
	v_mfma_f32_16x16x32_bf16 v[78:81], v[4:7], v[166:169], v[18:21]
	v_mfma_f32_16x16x32_bf16 v[18:21], v[182:185], v[82:85], v[230:233]
	v_mfma_f32_16x16x32_bf16 v[74:77], v[196:199], v[166:169], v[18:21]
	v_mfma_f32_16x16x32_bf16 v[18:21], v[0:3], v[170:173], v[54:57]
	v_mfma_f32_16x16x32_bf16 v[46:49], v[4:7], v[200:203], v[18:21]
	v_mfma_f32_16x16x32_bf16 v[18:21], v[182:185], v[170:173], v[50:53]
	v_mfma_f32_16x16x32_bf16 v[42:45], v[196:199], v[200:203], v[18:21]
	v_mfma_f32_16x16x32_bf16 v[18:21], v[0:3], v[204:207], v[234:237]
	v_mfma_f32_16x16x32_bf16 v[0:3], v[0:3], v[222:225], v[150:153]
	v_mfma_f32_16x16x32_bf16 v[22:25], v[4:7], v[218:221], v[18:21]
	v_mfma_f32_16x16x32_bf16 v[18:21], v[182:185], v[204:207], v[238:241]
	v_mfma_f32_16x16x32_bf16 v[4:7], v[4:7], v[250:253], v[0:3]
	v_mfma_f32_16x16x32_bf16 v[0:3], v[182:185], v[222:225], v[154:157]
	v_mfma_f32_16x16x32_bf16 v[18:21], v[196:199], v[218:221], v[18:21]
	v_mfma_f32_16x16x32_bf16 v[0:3], v[196:199], v[250:253], v[0:3]
	v_mfma_f32_16x16x32_bf16 v[26:29], v[242:245], v[82:85], v[26:29]
	v_mfma_f32_16x16x32_bf16 v[30:33], v[208:211], v[82:85], v[30:33]
	v_mfma_f32_16x16x32_bf16 v[82:85], v[246:249], v[166:169], v[26:29]
	v_mfma_f32_16x16x32_bf16 v[26:29], v[208:211], v[170:173], v[158:161]
	v_mfma_f32_16x16x32_bf16 v[54:57], v[214:217], v[200:203], v[26:29]
	v_mfma_f32_16x16x32_bf16 v[26:29], v[242:245], v[170:173], v[162:165]
	v_mfma_f32_16x16x32_bf16 v[8:11], v[242:245], v[204:207], v[8:11]
	v_mfma_f32_16x16x32_bf16 v[50:53], v[246:249], v[200:203], v[26:29]
	v_mfma_f32_16x16x32_bf16 v[12:15], v[208:211], v[204:207], v[12:15]
	v_mfma_f32_16x16x32_bf16 v[26:29], v[246:249], v[218:221], v[8:11]
	v_mfma_f32_16x16x32_bf16 v[8:11], v[208:211], v[222:225], v[174:177]
	v_mfma_f32_16x16x32_bf16 v[98:101], v[214:217], v[166:169], v[30:33]
	v_mfma_f32_16x16x32_bf16 v[30:33], v[214:217], v[218:221], v[12:15]
	v_mfma_f32_16x16x32_bf16 v[12:15], v[214:217], v[250:253], v[8:11]
	v_mfma_f32_16x16x32_bf16 v[8:11], v[242:245], v[222:225], v[178:181]
	v_mfma_f32_16x16x32_bf16 v[8:11], v[246:249], v[250:253], v[8:11]
	s_setprio 0
	s_movk_i32 s1, 0x100
	v_cmp_gt_u32_e32 vcc, s1, v144
	s_barrier
	s_and_saveexec_b64 s[12:13], vcc
	s_cbranch_execz .LBB0_649
	s_barrier
